# P6 GEMM-1: gated running sum kept in the f32 MFMA accumulators across the four branch units (acc *= g_j/g_j+1 at unit boundaries, no re-zeroing, no bf16 P round trip except once after branch 3); P7 ep
# speedup vs baseline: 1.0159x; 1.0159x over previous
.LBB0_1749:
	v_cndmask_b32_e64 v216, 0, 1, s[20:21]
	v_cmp_ne_u32_e64 s[8:9], 1, v216
	s_andn2_b64 vcc, exec, s[20:21]
	s_mov_b64 s[20:21], s[26:27]
	s_cbranch_vccnz .LBB0_1751
	s_ashr_i32 s19, s45, 31
	s_mul_hi_u32 s20, s12, s45
	s_mul_i32 s19, s12, s19
	s_add_i32 s19, s20, s19
	s_mul_i32 s20, s13, s45
	s_add_i32 s19, s19, s20
	s_mul_i32 s20, s12, s45
	s_add_u32 s22, s28, s20
	s_addc_u32 s23, s5, s19
	s_ashr_i32 s19, s18, 31
	s_lshl_b64 s[20:21], s[18:19], 24
	s_add_u32 s20, s22, s20
	s_addc_u32 s21, s23, s21

.LBB0_1753:
	s_andn2_b64 vcc, exec, s[14:15]
	s_cmp_lg_u32 s46, 0
	s_cbranch_scc1 .Lp6_nz1
	v_mov_b32_e32 v131, 0
	v_mov_b32_e32 v130, v131
	v_mov_b32_e32 v129, v131
	v_mov_b32_e32 v128, v131
	v_mov_b32_e32 v127, v131
	v_mov_b32_e32 v126, v131
	v_mov_b32_e32 v125, v131
	v_mov_b32_e32 v124, v131
	v_mov_b32_e32 v115, v131
	v_mov_b32_e32 v114, v131
	v_mov_b32_e32 v113, v131
	v_mov_b32_e32 v112, v131
	v_mov_b32_e32 v111, v131
	v_mov_b32_e32 v110, v131
	v_mov_b32_e32 v109, v131
	v_mov_b32_e32 v108, v131
	v_mov_b32_e32 v99, v131
	v_mov_b32_e32 v98, v131
	v_mov_b32_e32 v97, v131
	v_mov_b32_e32 v96, v131
	v_mov_b32_e32 v95, v131
	v_mov_b32_e32 v94, v131
	v_mov_b32_e32 v93, v131
	v_mov_b32_e32 v92, v131
	v_mov_b32_e32 v79, v131
	v_mov_b32_e32 v78, v131
	v_mov_b32_e32 v77, v131
	v_mov_b32_e32 v76, v131
	v_mov_b32_e32 v75, v131
	v_mov_b32_e32 v74, v131
	v_mov_b32_e32 v73, v131
	v_mov_b32_e32 v72, v131
	v_mov_b32_e32 v123, v131
	v_mov_b32_e32 v122, v131
	v_mov_b32_e32 v121, v131
	v_mov_b32_e32 v120, v131
	v_mov_b32_e32 v119, v131
	v_mov_b32_e32 v118, v131
	v_mov_b32_e32 v117, v131
	v_mov_b32_e32 v116, v131
	v_mov_b32_e32 v107, v131
	v_mov_b32_e32 v106, v131
	v_mov_b32_e32 v105, v131
	v_mov_b32_e32 v104, v131
	v_mov_b32_e32 v103, v131
	v_mov_b32_e32 v102, v131
	v_mov_b32_e32 v101, v131
	v_mov_b32_e32 v100, v131
	v_mov_b32_e32 v91, v131
	v_mov_b32_e32 v90, v131
	v_mov_b32_e32 v89, v131
	v_mov_b32_e32 v88, v131
	v_mov_b32_e32 v87, v131
	v_mov_b32_e32 v86, v131
	v_mov_b32_e32 v85, v131
	v_mov_b32_e32 v84, v131
	v_mov_b32_e32 v71, v131
	v_mov_b32_e32 v70, v131
	v_mov_b32_e32 v69, v131
	v_mov_b32_e32 v68, v131
	v_mov_b32_e32 v67, v131
	v_mov_b32_e32 v66, v131
	v_mov_b32_e32 v65, v131
	v_mov_b32_e32 v64, v131
	v_mov_b32_e32 v63, v131
	v_mov_b32_e32 v62, v131
	v_mov_b32_e32 v61, v131
	v_mov_b32_e32 v60, v131
	v_mov_b32_e32 v59, v131
	v_mov_b32_e32 v58, v131
	v_mov_b32_e32 v57, v131
	v_mov_b32_e32 v56, v131
	v_mov_b32_e32 v47, v131
	v_mov_b32_e32 v46, v131
	v_mov_b32_e32 v45, v131
	v_mov_b32_e32 v44, v131
	v_mov_b32_e32 v43, v131
	v_mov_b32_e32 v42, v131
	v_mov_b32_e32 v41, v131
	v_mov_b32_e32 v40, v131
	v_mov_b32_e32 v31, v131
	v_mov_b32_e32 v30, v131
	v_mov_b32_e32 v29, v131
	v_mov_b32_e32 v28, v131
	v_mov_b32_e32 v27, v131
	v_mov_b32_e32 v26, v131
	v_mov_b32_e32 v25, v131
	v_mov_b32_e32 v24, v131
	v_mov_b32_e32 v15, v131
	v_mov_b32_e32 v14, v131
	v_mov_b32_e32 v13, v131
	v_mov_b32_e32 v12, v131
	v_mov_b32_e32 v11, v131
	v_mov_b32_e32 v10, v131
	v_mov_b32_e32 v9, v131
	v_mov_b32_e32 v8, v131
	v_mov_b32_e32 v55, v131
	v_mov_b32_e32 v54, v131
	v_mov_b32_e32 v53, v131
	v_mov_b32_e32 v52, v131
	v_mov_b32_e32 v51, v131
	v_mov_b32_e32 v50, v131
	v_mov_b32_e32 v49, v131
	v_mov_b32_e32 v48, v131
	v_mov_b32_e32 v39, v131
	v_mov_b32_e32 v38, v131
	v_mov_b32_e32 v37, v131
	v_mov_b32_e32 v36, v131
	v_mov_b32_e32 v35, v131
	v_mov_b32_e32 v34, v131
	v_mov_b32_e32 v33, v131
	v_mov_b32_e32 v32, v131
	v_mov_b32_e32 v23, v131
	v_mov_b32_e32 v22, v131
	v_mov_b32_e32 v21, v131
	v_mov_b32_e32 v20, v131
	v_mov_b32_e32 v19, v131
	v_mov_b32_e32 v18, v131
	v_mov_b32_e32 v17, v131
	v_mov_b32_e32 v16, v131
	v_mov_b32_e32 v7, v131
	v_mov_b32_e32 v6, v131
	v_mov_b32_e32 v5, v131
	v_mov_b32_e32 v4, v131
	v_mov_b32_e32 v3, v131
	v_mov_b32_e32 v2, v131
	v_mov_b32_e32 v1, v131
	v_mov_b32_e32 v0, v131
.Lp6_nz1:
	s_cbranch_vccnz .LBB0_1757
	s_add_u32 s19, s24, 0x100
	s_addc_u32 s49, s25, 0
	s_add_u32 s8, s26, 0x80
	s_addc_u32 s9, s27, 0
	s_mov_b32 s24, 0
	s_cmp_lg_u32 s46, 0
	s_cbranch_scc1 .LBB0_1755
	v_mov_b32_e32 v0, 0
	v_mov_b32_e32 v1, v0
	v_mov_b32_e32 v2, v0
	v_mov_b32_e32 v3, v0
	v_mov_b32_e32 v4, v0
	v_mov_b32_e32 v5, v0
	v_mov_b32_e32 v6, v0
	v_mov_b32_e32 v7, v0
	v_mov_b32_e32 v16, v0
	v_mov_b32_e32 v17, v0
	v_mov_b32_e32 v18, v0
	v_mov_b32_e32 v19, v0
	v_mov_b32_e32 v20, v0
	v_mov_b32_e32 v21, v0
	v_mov_b32_e32 v22, v0
	v_mov_b32_e32 v23, v0
	v_mov_b32_e32 v32, v0
	v_mov_b32_e32 v33, v0
	v_mov_b32_e32 v34, v0
	v_mov_b32_e32 v35, v0
	v_mov_b32_e32 v36, v0
	v_mov_b32_e32 v37, v0
	v_mov_b32_e32 v38, v0
	v_mov_b32_e32 v39, v0
	v_mov_b32_e32 v48, v0
	v_mov_b32_e32 v49, v0
	v_mov_b32_e32 v50, v0
	v_mov_b32_e32 v51, v0
	v_mov_b32_e32 v52, v0
	v_mov_b32_e32 v53, v0
	v_mov_b32_e32 v54, v0
	v_mov_b32_e32 v55, v0
	v_mov_b32_e32 v8, v0
	v_mov_b32_e32 v9, v0
	v_mov_b32_e32 v10, v0
	v_mov_b32_e32 v11, v0
	v_mov_b32_e32 v12, v0
	v_mov_b32_e32 v13, v0
	v_mov_b32_e32 v14, v0
	v_mov_b32_e32 v15, v0
	v_mov_b32_e32 v24, v0
	v_mov_b32_e32 v25, v0
	v_mov_b32_e32 v26, v0
	v_mov_b32_e32 v27, v0
	v_mov_b32_e32 v28, v0
	v_mov_b32_e32 v29, v0
	v_mov_b32_e32 v30, v0
	v_mov_b32_e32 v31, v0
	v_mov_b32_e32 v40, v0
	v_mov_b32_e32 v41, v0
	v_mov_b32_e32 v42, v0
	v_mov_b32_e32 v43, v0
	v_mov_b32_e32 v44, v0
	v_mov_b32_e32 v45, v0
	v_mov_b32_e32 v46, v0
	v_mov_b32_e32 v47, v0
	v_mov_b32_e32 v56, v0
	v_mov_b32_e32 v57, v0
	v_mov_b32_e32 v58, v0
	v_mov_b32_e32 v59, v0
	v_mov_b32_e32 v60, v0
	v_mov_b32_e32 v61, v0
	v_mov_b32_e32 v62, v0
	v_mov_b32_e32 v63, v0
	v_mov_b32_e32 v64, v0
	v_mov_b32_e32 v65, v0
	v_mov_b32_e32 v66, v0
	v_mov_b32_e32 v67, v0
	v_mov_b32_e32 v68, v0
	v_mov_b32_e32 v69, v0
	v_mov_b32_e32 v70, v0
	v_mov_b32_e32 v71, v0
	v_mov_b32_e32 v84, v0
	v_mov_b32_e32 v85, v0
	v_mov_b32_e32 v86, v0
	v_mov_b32_e32 v87, v0
	v_mov_b32_e32 v88, v0
	v_mov_b32_e32 v89, v0
	v_mov_b32_e32 v90, v0
	v_mov_b32_e32 v91, v0
	v_mov_b32_e32 v100, v0
	v_mov_b32_e32 v101, v0
	v_mov_b32_e32 v102, v0
	v_mov_b32_e32 v103, v0
	v_mov_b32_e32 v104, v0
	v_mov_b32_e32 v105, v0
	v_mov_b32_e32 v106, v0
	v_mov_b32_e32 v107, v0
	v_mov_b32_e32 v116, v0
	v_mov_b32_e32 v117, v0
	v_mov_b32_e32 v118, v0
	v_mov_b32_e32 v119, v0
	v_mov_b32_e32 v120, v0
	v_mov_b32_e32 v121, v0
	v_mov_b32_e32 v122, v0
	v_mov_b32_e32 v123, v0
	v_mov_b32_e32 v72, v0
	v_mov_b32_e32 v73, v0
	v_mov_b32_e32 v74, v0
	v_mov_b32_e32 v75, v0
	v_mov_b32_e32 v76, v0
	v_mov_b32_e32 v77, v0
	v_mov_b32_e32 v78, v0
	v_mov_b32_e32 v79, v0
	v_mov_b32_e32 v92, v0
	v_mov_b32_e32 v93, v0
	v_mov_b32_e32 v94, v0
	v_mov_b32_e32 v95, v0
	v_mov_b32_e32 v96, v0
	v_mov_b32_e32 v97, v0
	v_mov_b32_e32 v98, v0
	v_mov_b32_e32 v99, v0
	v_mov_b32_e32 v108, v0
	v_mov_b32_e32 v109, v0
	v_mov_b32_e32 v110, v0
	v_mov_b32_e32 v111, v0
	v_mov_b32_e32 v112, v0
	v_mov_b32_e32 v113, v0
	v_mov_b32_e32 v114, v0
	v_mov_b32_e32 v115, v0
	v_mov_b32_e32 v124, v0
	v_mov_b32_e32 v125, v0
	v_mov_b32_e32 v126, v0
	v_mov_b32_e32 v127, v0
	v_mov_b32_e32 v128, v0
	v_mov_b32_e32 v129, v0
	v_mov_b32_e32 v130, v0
	v_mov_b32_e32 v131, v0

.LBB0_1757:
	s_cmp_eq_u32 s46, 3
	s_cbranch_scc1 .Lp6e_last
	s_load_dwordx2 s[2:3], s[62:63], 0xc0
	v_lshrrev_b32_e32 v164, 8, v208
	v_and_b32_e32 v165, 15, v208
	v_lshl_add_u32 v164, v164, 6, v165
	v_bfe_u32 v165, v208, 6, 2
	v_bfe_u32 v166, v208, 4, 2
	v_lshlrev_b32_e32 v165, 6, v165
	v_lshl_add_u32 v165, v166, 4, v165
	v_lshl_add_u32 v216, v164, 9, v165
	v_lshl_add_u32 v221, v164, 11, v165
	s_mul_i32 s0, s48, 49
	s_lshl_b32 s19, s46, 2
	s_add_i32 s0, s0, s19
	s_add_i32 s0, s0, s47
	s_add_i32 s0, s0, 29
	s_lshl_b32 s0, s0, 17
	s_lshl_b32 s19, s48, 19
	s_lshl_b32 s32, s47, 9
	s_add_i32 s19, s19, s32
	s_mov_b32 s60, 0xbfb8aa3b
	s_mov_b32 s61, 0xbfb8aa3b
	s_mov_b32 s78, 1.0
	s_mov_b32 s79, 1.0
	s_waitcnt lgkmcnt(0)
	s_add_u32 s24, s2, 0x74c2800
	s_addc_u32 s25, s3, 0
	s_add_u32 s24, s24, s0
	s_addc_u32 s25, s25, 0
	s_add_u32 s26, s2, 0x244c2800
	s_addc_u32 s27, s3, 0
	s_add_u32 s26, s26, s19
	s_addc_u32 s27, s27, 0
	s_add_u32 s8, s24, 0x0
	s_addc_u32 s9, s25, 0
	global_load_dwordx4 v[132:135], v216, s[8:9]
	s_add_u32 s8, s24, 0x80000
	s_addc_u32 s9, s25, 0
	global_load_dwordx4 v[148:151], v216, s[8:9]
	s_add_u32 s8, s24, 0x0
	s_addc_u32 s9, s25, 0
	global_load_dwordx4 v[136:139], v216, s[8:9] offset:256
	s_add_u32 s8, s24, 0x80000
	s_addc_u32 s9, s25, 0
	global_load_dwordx4 v[152:155], v216, s[8:9] offset:256
	s_add_u32 s8, s24, 0x2000
	s_addc_u32 s9, s25, 0
	global_load_dwordx4 v[140:143], v216, s[8:9]
	s_add_u32 s8, s24, 0x82000
	s_addc_u32 s9, s25, 0
	global_load_dwordx4 v[156:159], v216, s[8:9]
	s_add_u32 s8, s24, 0x2000
	s_addc_u32 s9, s25, 0
	global_load_dwordx4 v[144:147], v216, s[8:9] offset:256
	s_add_u32 s8, s24, 0x82000
	s_addc_u32 s9, s25, 0
	global_load_dwordx4 v[160:163], v216, s[8:9] offset:256
	s_add_u32 s8, s24, 0x4000
	s_addc_u32 s9, s25, 0
	global_load_dwordx4 v[224:227], v216, s[8:9]
	s_add_u32 s8, s24, 0x84000
	s_addc_u32 s9, s25, 0
	global_load_dwordx4 v[194:197], v216, s[8:9]
	s_add_u32 s8, s24, 0x4000
	s_addc_u32 s9, s25, 0
	global_load_dwordx4 v[228:231], v216, s[8:9] offset:256
	s_add_u32 s8, s24, 0x84000
	s_addc_u32 s9, s25, 0
	global_load_dwordx4 v[198:201], v216, s[8:9] offset:256
	s_add_u32 s8, s24, 0x6000
	s_addc_u32 s9, s25, 0
	global_load_dwordx4 v[232:235], v216, s[8:9]
	s_add_u32 s8, s24, 0x86000
	s_addc_u32 s9, s25, 0
	global_load_dwordx4 v[202:205], v216, s[8:9]
	s_add_u32 s8, s24, 0x6000
	s_addc_u32 s9, s25, 0
	global_load_dwordx4 v[236:239], v216, s[8:9] offset:256
	s_add_u32 s8, s24, 0x86000
	s_addc_u32 s9, s25, 0
	global_load_dwordx4 v[240:243], v216, s[8:9] offset:256
	s_waitcnt vmcnt(14)
	s_add_u32 s98, s26, 0x0
	s_addc_u32 s99, s27, 0
	v_lshlrev_b32_e32 v164, 16, v132
	v_lshlrev_b32_e32 v170, 16, v133
	v_lshlrev_b32_e32 v172, 16, v134
	v_lshlrev_b32_e32 v206, 16, v135
	v_and_b32_e32 v165, 0xffff0000, v132
	v_and_b32_e32 v171, 0xffff0000, v133
	v_and_b32_e32 v173, 0xffff0000, v134
	v_and_b32_e32 v207, 0xffff0000, v135
	v_lshlrev_b32_e32 v210, 16, v148
	v_lshlrev_b32_e32 v244, 16, v149
	v_lshlrev_b32_e32 v248, 16, v150
	v_lshlrev_b32_e32 v250, 16, v151
	v_and_b32_e32 v211, 0xffff0000, v148
	v_and_b32_e32 v245, 0xffff0000, v149
	v_and_b32_e32 v249, 0xffff0000, v150
	v_and_b32_e32 v251, 0xffff0000, v151
	v_pk_mul_f32 v[164:165], v[164:165], s[60:61]
	v_pk_mul_f32 v[170:171], v[170:171], s[60:61]
	v_pk_mul_f32 v[172:173], v[172:173], s[60:61]
	v_pk_mul_f32 v[206:207], v[206:207], s[60:61]
	v_pk_mul_f32 v[210:211], v[210:211], s[60:61]
	v_pk_mul_f32 v[244:245], v[244:245], s[60:61]
	v_pk_mul_f32 v[248:249], v[248:249], s[60:61]
	v_pk_mul_f32 v[250:251], v[250:251], s[60:61]
	v_exp_f32_e32 v164, v164
	v_exp_f32_e32 v170, v170
	v_exp_f32_e32 v172, v172
	v_exp_f32_e32 v206, v206
	v_exp_f32_e32 v165, v165
	v_exp_f32_e32 v171, v171
	v_exp_f32_e32 v173, v173
	v_exp_f32_e32 v207, v207
	v_exp_f32_e32 v210, v210
	v_exp_f32_e32 v244, v244
	v_exp_f32_e32 v248, v248
	v_exp_f32_e32 v250, v250
	v_exp_f32_e32 v211, v211
	v_exp_f32_e32 v245, v245
	v_exp_f32_e32 v249, v249
	v_exp_f32_e32 v251, v251
	v_pk_add_f32 v[164:165], v[164:165], s[78:79]
	v_pk_add_f32 v[170:171], v[170:171], s[78:79]
	v_pk_add_f32 v[172:173], v[172:173], s[78:79]
	v_pk_add_f32 v[206:207], v[206:207], s[78:79]
	v_pk_add_f32 v[210:211], v[210:211], s[78:79]
	v_pk_add_f32 v[244:245], v[244:245], s[78:79]
	v_pk_add_f32 v[248:249], v[248:249], s[78:79]
	v_pk_add_f32 v[250:251], v[250:251], s[78:79]
	v_rcp_f32_e32 v164, v164
	v_rcp_f32_e32 v170, v170
	v_rcp_f32_e32 v172, v172
	v_rcp_f32_e32 v206, v206
	v_rcp_f32_e32 v165, v165
	v_rcp_f32_e32 v171, v171
	v_rcp_f32_e32 v173, v173
	v_rcp_f32_e32 v207, v207
	s_nop 0
	v_pk_mul_f32 v[164:165], v[164:165], v[210:211]
	v_pk_mul_f32 v[170:171], v[170:171], v[244:245]
	v_pk_mul_f32 v[172:173], v[172:173], v[248:249]
	v_pk_mul_f32 v[206:207], v[206:207], v[250:251]
	v_pk_mul_f32 v[128:129], v[128:129], v[164:165]
	v_pk_mul_f32 v[130:131], v[130:131], v[170:171]
	v_pk_mul_f32 v[124:125], v[124:125], v[172:173]
	v_pk_mul_f32 v[126:127], v[126:127], v[206:207]
	s_add_u32 s8, s24, 0x10000
	s_addc_u32 s9, s25, 0
	global_load_dwordx4 v[132:135], v216, s[8:9]
	s_add_u32 s8, s24, 0x90000
	s_addc_u32 s9, s25, 0
	global_load_dwordx4 v[148:151], v216, s[8:9]
	s_waitcnt vmcnt(14)
	s_add_u32 s98, s26, 0x0
	s_addc_u32 s99, s27, 0
	v_lshlrev_b32_e32 v164, 16, v136
	v_lshlrev_b32_e32 v170, 16, v137
	v_lshlrev_b32_e32 v172, 16, v138
	v_lshlrev_b32_e32 v206, 16, v139
	v_and_b32_e32 v165, 0xffff0000, v136
	v_and_b32_e32 v171, 0xffff0000, v137
	v_and_b32_e32 v173, 0xffff0000, v138
	v_and_b32_e32 v207, 0xffff0000, v139
	v_lshlrev_b32_e32 v210, 16, v152
	v_lshlrev_b32_e32 v244, 16, v153
	v_lshlrev_b32_e32 v248, 16, v154
	v_lshlrev_b32_e32 v250, 16, v155
	v_and_b32_e32 v211, 0xffff0000, v152
	v_and_b32_e32 v245, 0xffff0000, v153
	v_and_b32_e32 v249, 0xffff0000, v154
	v_and_b32_e32 v251, 0xffff0000, v155
	v_pk_mul_f32 v[164:165], v[164:165], s[60:61]
	v_pk_mul_f32 v[170:171], v[170:171], s[60:61]
	v_pk_mul_f32 v[172:173], v[172:173], s[60:61]
	v_pk_mul_f32 v[206:207], v[206:207], s[60:61]
	v_pk_mul_f32 v[210:211], v[210:211], s[60:61]
	v_pk_mul_f32 v[244:245], v[244:245], s[60:61]
	v_pk_mul_f32 v[248:249], v[248:249], s[60:61]
	v_pk_mul_f32 v[250:251], v[250:251], s[60:61]
	v_exp_f32_e32 v164, v164
	v_exp_f32_e32 v170, v170
	v_exp_f32_e32 v172, v172
	v_exp_f32_e32 v206, v206
	v_exp_f32_e32 v165, v165
	v_exp_f32_e32 v171, v171
	v_exp_f32_e32 v173, v173
	v_exp_f32_e32 v207, v207
	v_exp_f32_e32 v210, v210
	v_exp_f32_e32 v244, v244
	v_exp_f32_e32 v248, v248
	v_exp_f32_e32 v250, v250
	v_exp_f32_e32 v211, v211
	v_exp_f32_e32 v245, v245
	v_exp_f32_e32 v249, v249
	v_exp_f32_e32 v251, v251
	v_pk_add_f32 v[164:165], v[164:165], s[78:79]
	v_pk_add_f32 v[170:171], v[170:171], s[78:79]
	v_pk_add_f32 v[172:173], v[172:173], s[78:79]
	v_pk_add_f32 v[206:207], v[206:207], s[78:79]
	v_pk_add_f32 v[210:211], v[210:211], s[78:79]
	v_pk_add_f32 v[244:245], v[244:245], s[78:79]
	v_pk_add_f32 v[248:249], v[248:249], s[78:79]
	v_pk_add_f32 v[250:251], v[250:251], s[78:79]
	v_rcp_f32_e32 v164, v164
	v_rcp_f32_e32 v170, v170
	v_rcp_f32_e32 v172, v172
	v_rcp_f32_e32 v206, v206
	v_rcp_f32_e32 v165, v165
	v_rcp_f32_e32 v171, v171
	v_rcp_f32_e32 v173, v173
	v_rcp_f32_e32 v207, v207
	s_nop 0
	v_pk_mul_f32 v[164:165], v[164:165], v[210:211]
	v_pk_mul_f32 v[170:171], v[170:171], v[244:245]
	v_pk_mul_f32 v[172:173], v[172:173], v[248:249]
	v_pk_mul_f32 v[206:207], v[206:207], v[250:251]
	v_pk_mul_f32 v[120:121], v[120:121], v[164:165]
	v_pk_mul_f32 v[122:123], v[122:123], v[170:171]
	v_pk_mul_f32 v[116:117], v[116:117], v[172:173]
	v_pk_mul_f32 v[118:119], v[118:119], v[206:207]
	s_add_u32 s8, s24, 0x10000
	s_addc_u32 s9, s25, 0
	global_load_dwordx4 v[136:139], v216, s[8:9] offset:256
	s_add_u32 s8, s24, 0x90000
	s_addc_u32 s9, s25, 0
	global_load_dwordx4 v[152:155], v216, s[8:9] offset:256
	s_waitcnt vmcnt(14)
	s_add_u32 s98, s26, 0x8000
	s_addc_u32 s99, s27, 0
	v_lshlrev_b32_e32 v164, 16, v140
	v_lshlrev_b32_e32 v170, 16, v141
	v_lshlrev_b32_e32 v172, 16, v142
	v_lshlrev_b32_e32 v206, 16, v143
	v_and_b32_e32 v165, 0xffff0000, v140
	v_and_b32_e32 v171, 0xffff0000, v141
	v_and_b32_e32 v173, 0xffff0000, v142
	v_and_b32_e32 v207, 0xffff0000, v143
	v_lshlrev_b32_e32 v210, 16, v156
	v_lshlrev_b32_e32 v244, 16, v157
	v_lshlrev_b32_e32 v248, 16, v158
	v_lshlrev_b32_e32 v250, 16, v159
	v_and_b32_e32 v211, 0xffff0000, v156
	v_and_b32_e32 v245, 0xffff0000, v157
	v_and_b32_e32 v249, 0xffff0000, v158
	v_and_b32_e32 v251, 0xffff0000, v159
	v_pk_mul_f32 v[164:165], v[164:165], s[60:61]
	v_pk_mul_f32 v[170:171], v[170:171], s[60:61]
	v_pk_mul_f32 v[172:173], v[172:173], s[60:61]
	v_pk_mul_f32 v[206:207], v[206:207], s[60:61]
	v_pk_mul_f32 v[210:211], v[210:211], s[60:61]
	v_pk_mul_f32 v[244:245], v[244:245], s[60:61]
	v_pk_mul_f32 v[248:249], v[248:249], s[60:61]
	v_pk_mul_f32 v[250:251], v[250:251], s[60:61]
	v_exp_f32_e32 v164, v164
	v_exp_f32_e32 v170, v170
	v_exp_f32_e32 v172, v172
	v_exp_f32_e32 v206, v206
	v_exp_f32_e32 v165, v165
	v_exp_f32_e32 v171, v171
	v_exp_f32_e32 v173, v173
	v_exp_f32_e32 v207, v207
	v_exp_f32_e32 v210, v210
	v_exp_f32_e32 v244, v244
	v_exp_f32_e32 v248, v248
	v_exp_f32_e32 v250, v250
	v_exp_f32_e32 v211, v211
	v_exp_f32_e32 v245, v245
	v_exp_f32_e32 v249, v249
	v_exp_f32_e32 v251, v251
	v_pk_add_f32 v[164:165], v[164:165], s[78:79]
	v_pk_add_f32 v[170:171], v[170:171], s[78:79]
	v_pk_add_f32 v[172:173], v[172:173], s[78:79]
	v_pk_add_f32 v[206:207], v[206:207], s[78:79]
	v_pk_add_f32 v[210:211], v[210:211], s[78:79]
	v_pk_add_f32 v[244:245], v[244:245], s[78:79]
	v_pk_add_f32 v[248:249], v[248:249], s[78:79]
	v_pk_add_f32 v[250:251], v[250:251], s[78:79]
	v_rcp_f32_e32 v164, v164
	v_rcp_f32_e32 v170, v170
	v_rcp_f32_e32 v172, v172
	v_rcp_f32_e32 v206, v206
	v_rcp_f32_e32 v165, v165
	v_rcp_f32_e32 v171, v171
	v_rcp_f32_e32 v173, v173
	v_rcp_f32_e32 v207, v207
	s_nop 0
	v_pk_mul_f32 v[164:165], v[164:165], v[210:211]
	v_pk_mul_f32 v[170:171], v[170:171], v[244:245]
	v_pk_mul_f32 v[172:173], v[172:173], v[248:249]
	v_pk_mul_f32 v[206:207], v[206:207], v[250:251]
	v_pk_mul_f32 v[112:113], v[112:113], v[164:165]
	v_pk_mul_f32 v[114:115], v[114:115], v[170:171]
	v_pk_mul_f32 v[108:109], v[108:109], v[172:173]
	v_pk_mul_f32 v[110:111], v[110:111], v[206:207]
	s_add_u32 s8, s24, 0x12000
	s_addc_u32 s9, s25, 0
	global_load_dwordx4 v[140:143], v216, s[8:9]
	s_add_u32 s8, s24, 0x92000
	s_addc_u32 s9, s25, 0
	global_load_dwordx4 v[156:159], v216, s[8:9]
	s_waitcnt vmcnt(14)
	s_add_u32 s98, s26, 0x8000
	s_addc_u32 s99, s27, 0
	v_lshlrev_b32_e32 v164, 16, v144
	v_lshlrev_b32_e32 v170, 16, v145
	v_lshlrev_b32_e32 v172, 16, v146
	v_lshlrev_b32_e32 v206, 16, v147
	v_and_b32_e32 v165, 0xffff0000, v144
	v_and_b32_e32 v171, 0xffff0000, v145
	v_and_b32_e32 v173, 0xffff0000, v146
	v_and_b32_e32 v207, 0xffff0000, v147
	v_lshlrev_b32_e32 v210, 16, v160
	v_lshlrev_b32_e32 v244, 16, v161
	v_lshlrev_b32_e32 v248, 16, v162
	v_lshlrev_b32_e32 v250, 16, v163
	v_and_b32_e32 v211, 0xffff0000, v160
	v_and_b32_e32 v245, 0xffff0000, v161
	v_and_b32_e32 v249, 0xffff0000, v162
	v_and_b32_e32 v251, 0xffff0000, v163
	v_pk_mul_f32 v[164:165], v[164:165], s[60:61]
	v_pk_mul_f32 v[170:171], v[170:171], s[60:61]
	v_pk_mul_f32 v[172:173], v[172:173], s[60:61]
	v_pk_mul_f32 v[206:207], v[206:207], s[60:61]
	v_pk_mul_f32 v[210:211], v[210:211], s[60:61]
	v_pk_mul_f32 v[244:245], v[244:245], s[60:61]
	v_pk_mul_f32 v[248:249], v[248:249], s[60:61]
	v_pk_mul_f32 v[250:251], v[250:251], s[60:61]
	v_exp_f32_e32 v164, v164
	v_exp_f32_e32 v170, v170
	v_exp_f32_e32 v172, v172
	v_exp_f32_e32 v206, v206
	v_exp_f32_e32 v165, v165
	v_exp_f32_e32 v171, v171
	v_exp_f32_e32 v173, v173
	v_exp_f32_e32 v207, v207
	v_exp_f32_e32 v210, v210
	v_exp_f32_e32 v244, v244
	v_exp_f32_e32 v248, v248
	v_exp_f32_e32 v250, v250
	v_exp_f32_e32 v211, v211
	v_exp_f32_e32 v245, v245
	v_exp_f32_e32 v249, v249
	v_exp_f32_e32 v251, v251
	v_pk_add_f32 v[164:165], v[164:165], s[78:79]
	v_pk_add_f32 v[170:171], v[170:171], s[78:79]
	v_pk_add_f32 v[172:173], v[172:173], s[78:79]
	v_pk_add_f32 v[206:207], v[206:207], s[78:79]
	v_pk_add_f32 v[210:211], v[210:211], s[78:79]
	v_pk_add_f32 v[244:245], v[244:245], s[78:79]
	v_pk_add_f32 v[248:249], v[248:249], s[78:79]
	v_pk_add_f32 v[250:251], v[250:251], s[78:79]
	v_rcp_f32_e32 v164, v164
	v_rcp_f32_e32 v170, v170
	v_rcp_f32_e32 v172, v172
	v_rcp_f32_e32 v206, v206
	v_rcp_f32_e32 v165, v165
	v_rcp_f32_e32 v171, v171
	v_rcp_f32_e32 v173, v173
	v_rcp_f32_e32 v207, v207
	s_nop 0
	v_pk_mul_f32 v[164:165], v[164:165], v[210:211]
	v_pk_mul_f32 v[170:171], v[170:171], v[244:245]
	v_pk_mul_f32 v[172:173], v[172:173], v[248:249]
	v_pk_mul_f32 v[206:207], v[206:207], v[250:251]
	v_pk_mul_f32 v[104:105], v[104:105], v[164:165]
	v_pk_mul_f32 v[106:107], v[106:107], v[170:171]
	v_pk_mul_f32 v[100:101], v[100:101], v[172:173]
	v_pk_mul_f32 v[102:103], v[102:103], v[206:207]
	s_add_u32 s8, s24, 0x12000
	s_addc_u32 s9, s25, 0
	global_load_dwordx4 v[144:147], v216, s[8:9] offset:256
	s_add_u32 s8, s24, 0x92000
	s_addc_u32 s9, s25, 0
	global_load_dwordx4 v[160:163], v216, s[8:9] offset:256
	s_waitcnt vmcnt(14)
	s_add_u32 s98, s26, 0x10000
	s_addc_u32 s99, s27, 0
	v_lshlrev_b32_e32 v164, 16, v224
	v_lshlrev_b32_e32 v170, 16, v225
	v_lshlrev_b32_e32 v172, 16, v226
	v_lshlrev_b32_e32 v206, 16, v227
	v_and_b32_e32 v165, 0xffff0000, v224
	v_and_b32_e32 v171, 0xffff0000, v225
	v_and_b32_e32 v173, 0xffff0000, v226
	v_and_b32_e32 v207, 0xffff0000, v227
	v_lshlrev_b32_e32 v210, 16, v194
	v_lshlrev_b32_e32 v244, 16, v195
	v_lshlrev_b32_e32 v248, 16, v196
	v_lshlrev_b32_e32 v250, 16, v197
	v_and_b32_e32 v211, 0xffff0000, v194
	v_and_b32_e32 v245, 0xffff0000, v195
	v_and_b32_e32 v249, 0xffff0000, v196
	v_and_b32_e32 v251, 0xffff0000, v197
	v_pk_mul_f32 v[164:165], v[164:165], s[60:61]
	v_pk_mul_f32 v[170:171], v[170:171], s[60:61]
	v_pk_mul_f32 v[172:173], v[172:173], s[60:61]
	v_pk_mul_f32 v[206:207], v[206:207], s[60:61]
	v_pk_mul_f32 v[210:211], v[210:211], s[60:61]
	v_pk_mul_f32 v[244:245], v[244:245], s[60:61]
	v_pk_mul_f32 v[248:249], v[248:249], s[60:61]
	v_pk_mul_f32 v[250:251], v[250:251], s[60:61]
	v_exp_f32_e32 v164, v164
	v_exp_f32_e32 v170, v170
	v_exp_f32_e32 v172, v172
	v_exp_f32_e32 v206, v206
	v_exp_f32_e32 v165, v165
	v_exp_f32_e32 v171, v171
	v_exp_f32_e32 v173, v173
	v_exp_f32_e32 v207, v207
	v_exp_f32_e32 v210, v210
	v_exp_f32_e32 v244, v244
	v_exp_f32_e32 v248, v248
	v_exp_f32_e32 v250, v250
	v_exp_f32_e32 v211, v211
	v_exp_f32_e32 v245, v245
	v_exp_f32_e32 v249, v249
	v_exp_f32_e32 v251, v251
	v_pk_add_f32 v[164:165], v[164:165], s[78:79]
	v_pk_add_f32 v[170:171], v[170:171], s[78:79]
	v_pk_add_f32 v[172:173], v[172:173], s[78:79]
	v_pk_add_f32 v[206:207], v[206:207], s[78:79]
	v_pk_add_f32 v[210:211], v[210:211], s[78:79]
	v_pk_add_f32 v[244:245], v[244:245], s[78:79]
	v_pk_add_f32 v[248:249], v[248:249], s[78:79]
	v_pk_add_f32 v[250:251], v[250:251], s[78:79]
	v_rcp_f32_e32 v164, v164
	v_rcp_f32_e32 v170, v170
	v_rcp_f32_e32 v172, v172
	v_rcp_f32_e32 v206, v206
	v_rcp_f32_e32 v165, v165
	v_rcp_f32_e32 v171, v171
	v_rcp_f32_e32 v173, v173
	v_rcp_f32_e32 v207, v207
	s_nop 0
	v_pk_mul_f32 v[164:165], v[164:165], v[210:211]
	v_pk_mul_f32 v[170:171], v[170:171], v[244:245]
	v_pk_mul_f32 v[172:173], v[172:173], v[248:249]
	v_pk_mul_f32 v[206:207], v[206:207], v[250:251]
	v_pk_mul_f32 v[96:97], v[96:97], v[164:165]
	v_pk_mul_f32 v[98:99], v[98:99], v[170:171]
	v_pk_mul_f32 v[92:93], v[92:93], v[172:173]
	v_pk_mul_f32 v[94:95], v[94:95], v[206:207]
	s_add_u32 s8, s24, 0x14000
	s_addc_u32 s9, s25, 0
	global_load_dwordx4 v[224:227], v216, s[8:9]
	s_add_u32 s8, s24, 0x94000
	s_addc_u32 s9, s25, 0
	global_load_dwordx4 v[194:197], v216, s[8:9]
	s_waitcnt vmcnt(14)
	s_add_u32 s98, s26, 0x10000
	s_addc_u32 s99, s27, 0
	v_lshlrev_b32_e32 v164, 16, v228
	v_lshlrev_b32_e32 v170, 16, v229
	v_lshlrev_b32_e32 v172, 16, v230
	v_lshlrev_b32_e32 v206, 16, v231
	v_and_b32_e32 v165, 0xffff0000, v228
	v_and_b32_e32 v171, 0xffff0000, v229
	v_and_b32_e32 v173, 0xffff0000, v230
	v_and_b32_e32 v207, 0xffff0000, v231
	v_lshlrev_b32_e32 v210, 16, v198
	v_lshlrev_b32_e32 v244, 16, v199
	v_lshlrev_b32_e32 v248, 16, v200
	v_lshlrev_b32_e32 v250, 16, v201
	v_and_b32_e32 v211, 0xffff0000, v198
	v_and_b32_e32 v245, 0xffff0000, v199
	v_and_b32_e32 v249, 0xffff0000, v200
	v_and_b32_e32 v251, 0xffff0000, v201
	v_pk_mul_f32 v[164:165], v[164:165], s[60:61]
	v_pk_mul_f32 v[170:171], v[170:171], s[60:61]
	v_pk_mul_f32 v[172:173], v[172:173], s[60:61]
	v_pk_mul_f32 v[206:207], v[206:207], s[60:61]
	v_pk_mul_f32 v[210:211], v[210:211], s[60:61]
	v_pk_mul_f32 v[244:245], v[244:245], s[60:61]
	v_pk_mul_f32 v[248:249], v[248:249], s[60:61]
	v_pk_mul_f32 v[250:251], v[250:251], s[60:61]
	v_exp_f32_e32 v164, v164
	v_exp_f32_e32 v170, v170
	v_exp_f32_e32 v172, v172
	v_exp_f32_e32 v206, v206
	v_exp_f32_e32 v165, v165
	v_exp_f32_e32 v171, v171
	v_exp_f32_e32 v173, v173
	v_exp_f32_e32 v207, v207
	v_exp_f32_e32 v210, v210
	v_exp_f32_e32 v244, v244
	v_exp_f32_e32 v248, v248
	v_exp_f32_e32 v250, v250
	v_exp_f32_e32 v211, v211
	v_exp_f32_e32 v245, v245
	v_exp_f32_e32 v249, v249
	v_exp_f32_e32 v251, v251
	v_pk_add_f32 v[164:165], v[164:165], s[78:79]
	v_pk_add_f32 v[170:171], v[170:171], s[78:79]
	v_pk_add_f32 v[172:173], v[172:173], s[78:79]
	v_pk_add_f32 v[206:207], v[206:207], s[78:79]
	v_pk_add_f32 v[210:211], v[210:211], s[78:79]
	v_pk_add_f32 v[244:245], v[244:245], s[78:79]
	v_pk_add_f32 v[248:249], v[248:249], s[78:79]
	v_pk_add_f32 v[250:251], v[250:251], s[78:79]
	v_rcp_f32_e32 v164, v164
	v_rcp_f32_e32 v170, v170
	v_rcp_f32_e32 v172, v172
	v_rcp_f32_e32 v206, v206
	v_rcp_f32_e32 v165, v165
	v_rcp_f32_e32 v171, v171
	v_rcp_f32_e32 v173, v173
	v_rcp_f32_e32 v207, v207
	s_nop 0
	v_pk_mul_f32 v[164:165], v[164:165], v[210:211]
	v_pk_mul_f32 v[170:171], v[170:171], v[244:245]
	v_pk_mul_f32 v[172:173], v[172:173], v[248:249]
	v_pk_mul_f32 v[206:207], v[206:207], v[250:251]
	v_pk_mul_f32 v[88:89], v[88:89], v[164:165]
	v_pk_mul_f32 v[90:91], v[90:91], v[170:171]
	v_pk_mul_f32 v[84:85], v[84:85], v[172:173]
	v_pk_mul_f32 v[86:87], v[86:87], v[206:207]
	s_add_u32 s8, s24, 0x14000
	s_addc_u32 s9, s25, 0
	global_load_dwordx4 v[228:231], v216, s[8:9] offset:256
	s_add_u32 s8, s24, 0x94000
	s_addc_u32 s9, s25, 0
	global_load_dwordx4 v[198:201], v216, s[8:9] offset:256
	s_waitcnt vmcnt(14)
	s_add_u32 s98, s26, 0x18000
	s_addc_u32 s99, s27, 0
	v_lshlrev_b32_e32 v164, 16, v232
	v_lshlrev_b32_e32 v170, 16, v233
	v_lshlrev_b32_e32 v172, 16, v234
	v_lshlrev_b32_e32 v206, 16, v235
	v_and_b32_e32 v165, 0xffff0000, v232
	v_and_b32_e32 v171, 0xffff0000, v233
	v_and_b32_e32 v173, 0xffff0000, v234
	v_and_b32_e32 v207, 0xffff0000, v235
	v_lshlrev_b32_e32 v210, 16, v202
	v_lshlrev_b32_e32 v244, 16, v203
	v_lshlrev_b32_e32 v248, 16, v204
	v_lshlrev_b32_e32 v250, 16, v205
	v_and_b32_e32 v211, 0xffff0000, v202
	v_and_b32_e32 v245, 0xffff0000, v203
	v_and_b32_e32 v249, 0xffff0000, v204
	v_and_b32_e32 v251, 0xffff0000, v205
	v_pk_mul_f32 v[164:165], v[164:165], s[60:61]
	v_pk_mul_f32 v[170:171], v[170:171], s[60:61]
	v_pk_mul_f32 v[172:173], v[172:173], s[60:61]
	v_pk_mul_f32 v[206:207], v[206:207], s[60:61]
	v_pk_mul_f32 v[210:211], v[210:211], s[60:61]
	v_pk_mul_f32 v[244:245], v[244:245], s[60:61]
	v_pk_mul_f32 v[248:249], v[248:249], s[60:61]
	v_pk_mul_f32 v[250:251], v[250:251], s[60:61]
	v_exp_f32_e32 v164, v164
	v_exp_f32_e32 v170, v170
	v_exp_f32_e32 v172, v172
	v_exp_f32_e32 v206, v206
	v_exp_f32_e32 v165, v165
	v_exp_f32_e32 v171, v171
	v_exp_f32_e32 v173, v173
	v_exp_f32_e32 v207, v207
	v_exp_f32_e32 v210, v210
	v_exp_f32_e32 v244, v244
	v_exp_f32_e32 v248, v248
	v_exp_f32_e32 v250, v250
	v_exp_f32_e32 v211, v211
	v_exp_f32_e32 v245, v245
	v_exp_f32_e32 v249, v249
	v_exp_f32_e32 v251, v251
	v_pk_add_f32 v[164:165], v[164:165], s[78:79]
	v_pk_add_f32 v[170:171], v[170:171], s[78:79]
	v_pk_add_f32 v[172:173], v[172:173], s[78:79]
	v_pk_add_f32 v[206:207], v[206:207], s[78:79]
	v_pk_add_f32 v[210:211], v[210:211], s[78:79]
	v_pk_add_f32 v[244:245], v[244:245], s[78:79]
	v_pk_add_f32 v[248:249], v[248:249], s[78:79]
	v_pk_add_f32 v[250:251], v[250:251], s[78:79]
	v_rcp_f32_e32 v164, v164
	v_rcp_f32_e32 v170, v170
	v_rcp_f32_e32 v172, v172
	v_rcp_f32_e32 v206, v206
	v_rcp_f32_e32 v165, v165
	v_rcp_f32_e32 v171, v171
	v_rcp_f32_e32 v173, v173
	v_rcp_f32_e32 v207, v207
	s_nop 0
	v_pk_mul_f32 v[164:165], v[164:165], v[210:211]
	v_pk_mul_f32 v[170:171], v[170:171], v[244:245]
	v_pk_mul_f32 v[172:173], v[172:173], v[248:249]
	v_pk_mul_f32 v[206:207], v[206:207], v[250:251]
	v_pk_mul_f32 v[76:77], v[76:77], v[164:165]
	v_pk_mul_f32 v[78:79], v[78:79], v[170:171]
	v_pk_mul_f32 v[72:73], v[72:73], v[172:173]
	v_pk_mul_f32 v[74:75], v[74:75], v[206:207]
	s_add_u32 s8, s24, 0x16000
	s_addc_u32 s9, s25, 0
	global_load_dwordx4 v[232:235], v216, s[8:9]
	s_add_u32 s8, s24, 0x96000
	s_addc_u32 s9, s25, 0
	global_load_dwordx4 v[202:205], v216, s[8:9]
	s_waitcnt vmcnt(14)
	s_add_u32 s98, s26, 0x18000
	s_addc_u32 s99, s27, 0
	v_lshlrev_b32_e32 v164, 16, v236
	v_lshlrev_b32_e32 v170, 16, v237
	v_lshlrev_b32_e32 v172, 16, v238
	v_lshlrev_b32_e32 v206, 16, v239
	v_and_b32_e32 v165, 0xffff0000, v236
	v_and_b32_e32 v171, 0xffff0000, v237
	v_and_b32_e32 v173, 0xffff0000, v238
	v_and_b32_e32 v207, 0xffff0000, v239
	v_lshlrev_b32_e32 v210, 16, v240
	v_lshlrev_b32_e32 v244, 16, v241
	v_lshlrev_b32_e32 v248, 16, v242
	v_lshlrev_b32_e32 v250, 16, v243
	v_and_b32_e32 v211, 0xffff0000, v240
	v_and_b32_e32 v245, 0xffff0000, v241
	v_and_b32_e32 v249, 0xffff0000, v242
	v_and_b32_e32 v251, 0xffff0000, v243
	v_pk_mul_f32 v[164:165], v[164:165], s[60:61]
	v_pk_mul_f32 v[170:171], v[170:171], s[60:61]
	v_pk_mul_f32 v[172:173], v[172:173], s[60:61]
	v_pk_mul_f32 v[206:207], v[206:207], s[60:61]
	v_pk_mul_f32 v[210:211], v[210:211], s[60:61]
	v_pk_mul_f32 v[244:245], v[244:245], s[60:61]
	v_pk_mul_f32 v[248:249], v[248:249], s[60:61]
	v_pk_mul_f32 v[250:251], v[250:251], s[60:61]
	v_exp_f32_e32 v164, v164
	v_exp_f32_e32 v170, v170
	v_exp_f32_e32 v172, v172
	v_exp_f32_e32 v206, v206
	v_exp_f32_e32 v165, v165
	v_exp_f32_e32 v171, v171
	v_exp_f32_e32 v173, v173
	v_exp_f32_e32 v207, v207
	v_exp_f32_e32 v210, v210
	v_exp_f32_e32 v244, v244
	v_exp_f32_e32 v248, v248
	v_exp_f32_e32 v250, v250
	v_exp_f32_e32 v211, v211
	v_exp_f32_e32 v245, v245
	v_exp_f32_e32 v249, v249
	v_exp_f32_e32 v251, v251
	v_pk_add_f32 v[164:165], v[164:165], s[78:79]
	v_pk_add_f32 v[170:171], v[170:171], s[78:79]
	v_pk_add_f32 v[172:173], v[172:173], s[78:79]
	v_pk_add_f32 v[206:207], v[206:207], s[78:79]
	v_pk_add_f32 v[210:211], v[210:211], s[78:79]
	v_pk_add_f32 v[244:245], v[244:245], s[78:79]
	v_pk_add_f32 v[248:249], v[248:249], s[78:79]
	v_pk_add_f32 v[250:251], v[250:251], s[78:79]
	v_rcp_f32_e32 v164, v164
	v_rcp_f32_e32 v170, v170
	v_rcp_f32_e32 v172, v172
	v_rcp_f32_e32 v206, v206
	v_rcp_f32_e32 v165, v165
	v_rcp_f32_e32 v171, v171
	v_rcp_f32_e32 v173, v173
	v_rcp_f32_e32 v207, v207
	s_nop 0
	v_pk_mul_f32 v[164:165], v[164:165], v[210:211]
	v_pk_mul_f32 v[170:171], v[170:171], v[244:245]
	v_pk_mul_f32 v[172:173], v[172:173], v[248:249]
	v_pk_mul_f32 v[206:207], v[206:207], v[250:251]
	v_pk_mul_f32 v[68:69], v[68:69], v[164:165]
	v_pk_mul_f32 v[70:71], v[70:71], v[170:171]
	v_pk_mul_f32 v[64:65], v[64:65], v[172:173]
	v_pk_mul_f32 v[66:67], v[66:67], v[206:207]
	s_add_u32 s8, s24, 0x16000
	s_addc_u32 s9, s25, 0
	global_load_dwordx4 v[236:239], v216, s[8:9] offset:256
	s_add_u32 s8, s24, 0x96000
	s_addc_u32 s9, s25, 0
	global_load_dwordx4 v[240:243], v216, s[8:9] offset:256
	s_waitcnt vmcnt(14)
	s_add_u32 s98, s26, 0x40000
	s_addc_u32 s99, s27, 0
	v_lshlrev_b32_e32 v164, 16, v132
	v_lshlrev_b32_e32 v170, 16, v133
	v_lshlrev_b32_e32 v172, 16, v134
	v_lshlrev_b32_e32 v206, 16, v135
	v_and_b32_e32 v165, 0xffff0000, v132
	v_and_b32_e32 v171, 0xffff0000, v133
	v_and_b32_e32 v173, 0xffff0000, v134
	v_and_b32_e32 v207, 0xffff0000, v135
	v_lshlrev_b32_e32 v210, 16, v148
	v_lshlrev_b32_e32 v244, 16, v149
	v_lshlrev_b32_e32 v248, 16, v150
	v_lshlrev_b32_e32 v250, 16, v151
	v_and_b32_e32 v211, 0xffff0000, v148
	v_and_b32_e32 v245, 0xffff0000, v149
	v_and_b32_e32 v249, 0xffff0000, v150
	v_and_b32_e32 v251, 0xffff0000, v151
	v_pk_mul_f32 v[164:165], v[164:165], s[60:61]
	v_pk_mul_f32 v[170:171], v[170:171], s[60:61]
	v_pk_mul_f32 v[172:173], v[172:173], s[60:61]
	v_pk_mul_f32 v[206:207], v[206:207], s[60:61]
	v_pk_mul_f32 v[210:211], v[210:211], s[60:61]
	v_pk_mul_f32 v[244:245], v[244:245], s[60:61]
	v_pk_mul_f32 v[248:249], v[248:249], s[60:61]
	v_pk_mul_f32 v[250:251], v[250:251], s[60:61]
	v_exp_f32_e32 v164, v164
	v_exp_f32_e32 v170, v170
	v_exp_f32_e32 v172, v172
	v_exp_f32_e32 v206, v206
	v_exp_f32_e32 v165, v165
	v_exp_f32_e32 v171, v171
	v_exp_f32_e32 v173, v173
	v_exp_f32_e32 v207, v207
	v_exp_f32_e32 v210, v210
	v_exp_f32_e32 v244, v244
	v_exp_f32_e32 v248, v248
	v_exp_f32_e32 v250, v250
	v_exp_f32_e32 v211, v211
	v_exp_f32_e32 v245, v245
	v_exp_f32_e32 v249, v249
	v_exp_f32_e32 v251, v251
	v_pk_add_f32 v[164:165], v[164:165], s[78:79]
	v_pk_add_f32 v[170:171], v[170:171], s[78:79]
	v_pk_add_f32 v[172:173], v[172:173], s[78:79]
	v_pk_add_f32 v[206:207], v[206:207], s[78:79]
	v_pk_add_f32 v[210:211], v[210:211], s[78:79]
	v_pk_add_f32 v[244:245], v[244:245], s[78:79]
	v_pk_add_f32 v[248:249], v[248:249], s[78:79]
	v_pk_add_f32 v[250:251], v[250:251], s[78:79]
	v_rcp_f32_e32 v164, v164
	v_rcp_f32_e32 v170, v170
	v_rcp_f32_e32 v172, v172
	v_rcp_f32_e32 v206, v206
	v_rcp_f32_e32 v165, v165
	v_rcp_f32_e32 v171, v171
	v_rcp_f32_e32 v173, v173
	v_rcp_f32_e32 v207, v207
	s_nop 0
	v_pk_mul_f32 v[164:165], v[164:165], v[210:211]
	v_pk_mul_f32 v[170:171], v[170:171], v[244:245]
	v_pk_mul_f32 v[172:173], v[172:173], v[248:249]
	v_pk_mul_f32 v[206:207], v[206:207], v[250:251]
	v_pk_mul_f32 v[60:61], v[60:61], v[164:165]
	v_pk_mul_f32 v[62:63], v[62:63], v[170:171]
	v_pk_mul_f32 v[56:57], v[56:57], v[172:173]
	v_pk_mul_f32 v[58:59], v[58:59], v[206:207]
	s_waitcnt vmcnt(12)
	s_add_u32 s98, s26, 0x40000
	s_addc_u32 s99, s27, 0
	v_lshlrev_b32_e32 v164, 16, v136
	v_lshlrev_b32_e32 v170, 16, v137
	v_lshlrev_b32_e32 v172, 16, v138
	v_lshlrev_b32_e32 v206, 16, v139
	v_and_b32_e32 v165, 0xffff0000, v136
	v_and_b32_e32 v171, 0xffff0000, v137
	v_and_b32_e32 v173, 0xffff0000, v138
	v_and_b32_e32 v207, 0xffff0000, v139
	v_lshlrev_b32_e32 v210, 16, v152
	v_lshlrev_b32_e32 v244, 16, v153
	v_lshlrev_b32_e32 v248, 16, v154
	v_lshlrev_b32_e32 v250, 16, v155
	v_and_b32_e32 v211, 0xffff0000, v152
	v_and_b32_e32 v245, 0xffff0000, v153
	v_and_b32_e32 v249, 0xffff0000, v154
	v_and_b32_e32 v251, 0xffff0000, v155
	v_pk_mul_f32 v[164:165], v[164:165], s[60:61]
	v_pk_mul_f32 v[170:171], v[170:171], s[60:61]
	v_pk_mul_f32 v[172:173], v[172:173], s[60:61]
	v_pk_mul_f32 v[206:207], v[206:207], s[60:61]
	v_pk_mul_f32 v[210:211], v[210:211], s[60:61]
	v_pk_mul_f32 v[244:245], v[244:245], s[60:61]
	v_pk_mul_f32 v[248:249], v[248:249], s[60:61]
	v_pk_mul_f32 v[250:251], v[250:251], s[60:61]
	v_exp_f32_e32 v164, v164
	v_exp_f32_e32 v170, v170
	v_exp_f32_e32 v172, v172
	v_exp_f32_e32 v206, v206
	v_exp_f32_e32 v165, v165
	v_exp_f32_e32 v171, v171
	v_exp_f32_e32 v173, v173
	v_exp_f32_e32 v207, v207
	v_exp_f32_e32 v210, v210
	v_exp_f32_e32 v244, v244
	v_exp_f32_e32 v248, v248
	v_exp_f32_e32 v250, v250
	v_exp_f32_e32 v211, v211
	v_exp_f32_e32 v245, v245
	v_exp_f32_e32 v249, v249
	v_exp_f32_e32 v251, v251
	v_pk_add_f32 v[164:165], v[164:165], s[78:79]
	v_pk_add_f32 v[170:171], v[170:171], s[78:79]
	v_pk_add_f32 v[172:173], v[172:173], s[78:79]
	v_pk_add_f32 v[206:207], v[206:207], s[78:79]
	v_pk_add_f32 v[210:211], v[210:211], s[78:79]
	v_pk_add_f32 v[244:245], v[244:245], s[78:79]
	v_pk_add_f32 v[248:249], v[248:249], s[78:79]
	v_pk_add_f32 v[250:251], v[250:251], s[78:79]
	v_rcp_f32_e32 v164, v164
	v_rcp_f32_e32 v170, v170
	v_rcp_f32_e32 v172, v172
	v_rcp_f32_e32 v206, v206
	v_rcp_f32_e32 v165, v165
	v_rcp_f32_e32 v171, v171
	v_rcp_f32_e32 v173, v173
	v_rcp_f32_e32 v207, v207
	s_nop 0
	v_pk_mul_f32 v[164:165], v[164:165], v[210:211]
	v_pk_mul_f32 v[170:171], v[170:171], v[244:245]
	v_pk_mul_f32 v[172:173], v[172:173], v[248:249]
	v_pk_mul_f32 v[206:207], v[206:207], v[250:251]
	v_pk_mul_f32 v[52:53], v[52:53], v[164:165]
	v_pk_mul_f32 v[54:55], v[54:55], v[170:171]
	v_pk_mul_f32 v[48:49], v[48:49], v[172:173]
	v_pk_mul_f32 v[50:51], v[50:51], v[206:207]
	s_waitcnt vmcnt(10)
	s_add_u32 s98, s26, 0x48000
	s_addc_u32 s99, s27, 0
	v_lshlrev_b32_e32 v164, 16, v140
	v_lshlrev_b32_e32 v170, 16, v141
	v_lshlrev_b32_e32 v172, 16, v142
	v_lshlrev_b32_e32 v206, 16, v143
	v_and_b32_e32 v165, 0xffff0000, v140
	v_and_b32_e32 v171, 0xffff0000, v141
	v_and_b32_e32 v173, 0xffff0000, v142
	v_and_b32_e32 v207, 0xffff0000, v143
	v_lshlrev_b32_e32 v210, 16, v156
	v_lshlrev_b32_e32 v244, 16, v157
	v_lshlrev_b32_e32 v248, 16, v158
	v_lshlrev_b32_e32 v250, 16, v159
	v_and_b32_e32 v211, 0xffff0000, v156
	v_and_b32_e32 v245, 0xffff0000, v157
	v_and_b32_e32 v249, 0xffff0000, v158
	v_and_b32_e32 v251, 0xffff0000, v159
	v_pk_mul_f32 v[164:165], v[164:165], s[60:61]
	v_pk_mul_f32 v[170:171], v[170:171], s[60:61]
	v_pk_mul_f32 v[172:173], v[172:173], s[60:61]
	v_pk_mul_f32 v[206:207], v[206:207], s[60:61]
	v_pk_mul_f32 v[210:211], v[210:211], s[60:61]
	v_pk_mul_f32 v[244:245], v[244:245], s[60:61]
	v_pk_mul_f32 v[248:249], v[248:249], s[60:61]
	v_pk_mul_f32 v[250:251], v[250:251], s[60:61]
	v_exp_f32_e32 v164, v164
	v_exp_f32_e32 v170, v170
	v_exp_f32_e32 v172, v172
	v_exp_f32_e32 v206, v206
	v_exp_f32_e32 v165, v165
	v_exp_f32_e32 v171, v171
	v_exp_f32_e32 v173, v173
	v_exp_f32_e32 v207, v207
	v_exp_f32_e32 v210, v210
	v_exp_f32_e32 v244, v244
	v_exp_f32_e32 v248, v248
	v_exp_f32_e32 v250, v250
	v_exp_f32_e32 v211, v211
	v_exp_f32_e32 v245, v245
	v_exp_f32_e32 v249, v249
	v_exp_f32_e32 v251, v251
	v_pk_add_f32 v[164:165], v[164:165], s[78:79]
	v_pk_add_f32 v[170:171], v[170:171], s[78:79]
	v_pk_add_f32 v[172:173], v[172:173], s[78:79]
	v_pk_add_f32 v[206:207], v[206:207], s[78:79]
	v_pk_add_f32 v[210:211], v[210:211], s[78:79]
	v_pk_add_f32 v[244:245], v[244:245], s[78:79]
	v_pk_add_f32 v[248:249], v[248:249], s[78:79]
	v_pk_add_f32 v[250:251], v[250:251], s[78:79]
	v_rcp_f32_e32 v164, v164
	v_rcp_f32_e32 v170, v170
	v_rcp_f32_e32 v172, v172
	v_rcp_f32_e32 v206, v206
	v_rcp_f32_e32 v165, v165
	v_rcp_f32_e32 v171, v171
	v_rcp_f32_e32 v173, v173
	v_rcp_f32_e32 v207, v207
	s_nop 0
	v_pk_mul_f32 v[164:165], v[164:165], v[210:211]
	v_pk_mul_f32 v[170:171], v[170:171], v[244:245]
	v_pk_mul_f32 v[172:173], v[172:173], v[248:249]
	v_pk_mul_f32 v[206:207], v[206:207], v[250:251]
	v_pk_mul_f32 v[44:45], v[44:45], v[164:165]
	v_pk_mul_f32 v[46:47], v[46:47], v[170:171]
	v_pk_mul_f32 v[40:41], v[40:41], v[172:173]
	v_pk_mul_f32 v[42:43], v[42:43], v[206:207]
	s_waitcnt vmcnt(8)
	s_add_u32 s98, s26, 0x48000
	s_addc_u32 s99, s27, 0
	v_lshlrev_b32_e32 v164, 16, v144
	v_lshlrev_b32_e32 v170, 16, v145
	v_lshlrev_b32_e32 v172, 16, v146
	v_lshlrev_b32_e32 v206, 16, v147
	v_and_b32_e32 v165, 0xffff0000, v144
	v_and_b32_e32 v171, 0xffff0000, v145
	v_and_b32_e32 v173, 0xffff0000, v146
	v_and_b32_e32 v207, 0xffff0000, v147
	v_lshlrev_b32_e32 v210, 16, v160
	v_lshlrev_b32_e32 v244, 16, v161
	v_lshlrev_b32_e32 v248, 16, v162
	v_lshlrev_b32_e32 v250, 16, v163
	v_and_b32_e32 v211, 0xffff0000, v160
	v_and_b32_e32 v245, 0xffff0000, v161
	v_and_b32_e32 v249, 0xffff0000, v162
	v_and_b32_e32 v251, 0xffff0000, v163
	v_pk_mul_f32 v[164:165], v[164:165], s[60:61]
	v_pk_mul_f32 v[170:171], v[170:171], s[60:61]
	v_pk_mul_f32 v[172:173], v[172:173], s[60:61]
	v_pk_mul_f32 v[206:207], v[206:207], s[60:61]
	v_pk_mul_f32 v[210:211], v[210:211], s[60:61]
	v_pk_mul_f32 v[244:245], v[244:245], s[60:61]
	v_pk_mul_f32 v[248:249], v[248:249], s[60:61]
	v_pk_mul_f32 v[250:251], v[250:251], s[60:61]
	v_exp_f32_e32 v164, v164
	v_exp_f32_e32 v170, v170
	v_exp_f32_e32 v172, v172
	v_exp_f32_e32 v206, v206
	v_exp_f32_e32 v165, v165
	v_exp_f32_e32 v171, v171
	v_exp_f32_e32 v173, v173
	v_exp_f32_e32 v207, v207
	v_exp_f32_e32 v210, v210
	v_exp_f32_e32 v244, v244
	v_exp_f32_e32 v248, v248
	v_exp_f32_e32 v250, v250
	v_exp_f32_e32 v211, v211
	v_exp_f32_e32 v245, v245
	v_exp_f32_e32 v249, v249
	v_exp_f32_e32 v251, v251
	v_pk_add_f32 v[164:165], v[164:165], s[78:79]
	v_pk_add_f32 v[170:171], v[170:171], s[78:79]
	v_pk_add_f32 v[172:173], v[172:173], s[78:79]
	v_pk_add_f32 v[206:207], v[206:207], s[78:79]
	v_pk_add_f32 v[210:211], v[210:211], s[78:79]
	v_pk_add_f32 v[244:245], v[244:245], s[78:79]
	v_pk_add_f32 v[248:249], v[248:249], s[78:79]
	v_pk_add_f32 v[250:251], v[250:251], s[78:79]
	v_rcp_f32_e32 v164, v164
	v_rcp_f32_e32 v170, v170
	v_rcp_f32_e32 v172, v172
	v_rcp_f32_e32 v206, v206
	v_rcp_f32_e32 v165, v165
	v_rcp_f32_e32 v171, v171
	v_rcp_f32_e32 v173, v173
	v_rcp_f32_e32 v207, v207
	s_nop 0
	v_pk_mul_f32 v[164:165], v[164:165], v[210:211]
	v_pk_mul_f32 v[170:171], v[170:171], v[244:245]
	v_pk_mul_f32 v[172:173], v[172:173], v[248:249]
	v_pk_mul_f32 v[206:207], v[206:207], v[250:251]
	v_pk_mul_f32 v[36:37], v[36:37], v[164:165]
	v_pk_mul_f32 v[38:39], v[38:39], v[170:171]
	v_pk_mul_f32 v[32:33], v[32:33], v[172:173]
	v_pk_mul_f32 v[34:35], v[34:35], v[206:207]
	s_waitcnt vmcnt(6)
	s_add_u32 s98, s26, 0x50000
	s_addc_u32 s99, s27, 0
	v_lshlrev_b32_e32 v164, 16, v224
	v_lshlrev_b32_e32 v170, 16, v225
	v_lshlrev_b32_e32 v172, 16, v226
	v_lshlrev_b32_e32 v206, 16, v227
	v_and_b32_e32 v165, 0xffff0000, v224
	v_and_b32_e32 v171, 0xffff0000, v225
	v_and_b32_e32 v173, 0xffff0000, v226
	v_and_b32_e32 v207, 0xffff0000, v227
	v_lshlrev_b32_e32 v210, 16, v194
	v_lshlrev_b32_e32 v244, 16, v195
	v_lshlrev_b32_e32 v248, 16, v196
	v_lshlrev_b32_e32 v250, 16, v197
	v_and_b32_e32 v211, 0xffff0000, v194
	v_and_b32_e32 v245, 0xffff0000, v195
	v_and_b32_e32 v249, 0xffff0000, v196
	v_and_b32_e32 v251, 0xffff0000, v197
	v_pk_mul_f32 v[164:165], v[164:165], s[60:61]
	v_pk_mul_f32 v[170:171], v[170:171], s[60:61]
	v_pk_mul_f32 v[172:173], v[172:173], s[60:61]
	v_pk_mul_f32 v[206:207], v[206:207], s[60:61]
	v_pk_mul_f32 v[210:211], v[210:211], s[60:61]
	v_pk_mul_f32 v[244:245], v[244:245], s[60:61]
	v_pk_mul_f32 v[248:249], v[248:249], s[60:61]
	v_pk_mul_f32 v[250:251], v[250:251], s[60:61]
	v_exp_f32_e32 v164, v164
	v_exp_f32_e32 v170, v170
	v_exp_f32_e32 v172, v172
	v_exp_f32_e32 v206, v206
	v_exp_f32_e32 v165, v165
	v_exp_f32_e32 v171, v171
	v_exp_f32_e32 v173, v173
	v_exp_f32_e32 v207, v207
	v_exp_f32_e32 v210, v210
	v_exp_f32_e32 v244, v244
	v_exp_f32_e32 v248, v248
	v_exp_f32_e32 v250, v250
	v_exp_f32_e32 v211, v211
	v_exp_f32_e32 v245, v245
	v_exp_f32_e32 v249, v249
	v_exp_f32_e32 v251, v251
	v_pk_add_f32 v[164:165], v[164:165], s[78:79]
	v_pk_add_f32 v[170:171], v[170:171], s[78:79]
	v_pk_add_f32 v[172:173], v[172:173], s[78:79]
	v_pk_add_f32 v[206:207], v[206:207], s[78:79]
	v_pk_add_f32 v[210:211], v[210:211], s[78:79]
	v_pk_add_f32 v[244:245], v[244:245], s[78:79]
	v_pk_add_f32 v[248:249], v[248:249], s[78:79]
	v_pk_add_f32 v[250:251], v[250:251], s[78:79]
	v_rcp_f32_e32 v164, v164
	v_rcp_f32_e32 v170, v170
	v_rcp_f32_e32 v172, v172
	v_rcp_f32_e32 v206, v206
	v_rcp_f32_e32 v165, v165
	v_rcp_f32_e32 v171, v171
	v_rcp_f32_e32 v173, v173
	v_rcp_f32_e32 v207, v207
	s_nop 0
	v_pk_mul_f32 v[164:165], v[164:165], v[210:211]
	v_pk_mul_f32 v[170:171], v[170:171], v[244:245]
	v_pk_mul_f32 v[172:173], v[172:173], v[248:249]
	v_pk_mul_f32 v[206:207], v[206:207], v[250:251]
	v_pk_mul_f32 v[28:29], v[28:29], v[164:165]
	v_pk_mul_f32 v[30:31], v[30:31], v[170:171]
	v_pk_mul_f32 v[24:25], v[24:25], v[172:173]
	v_pk_mul_f32 v[26:27], v[26:27], v[206:207]
	s_waitcnt vmcnt(4)
	s_add_u32 s98, s26, 0x50000
	s_addc_u32 s99, s27, 0
	v_lshlrev_b32_e32 v164, 16, v228
	v_lshlrev_b32_e32 v170, 16, v229
	v_lshlrev_b32_e32 v172, 16, v230
	v_lshlrev_b32_e32 v206, 16, v231
	v_and_b32_e32 v165, 0xffff0000, v228
	v_and_b32_e32 v171, 0xffff0000, v229
	v_and_b32_e32 v173, 0xffff0000, v230
	v_and_b32_e32 v207, 0xffff0000, v231
	v_lshlrev_b32_e32 v210, 16, v198
	v_lshlrev_b32_e32 v244, 16, v199
	v_lshlrev_b32_e32 v248, 16, v200
	v_lshlrev_b32_e32 v250, 16, v201
	v_and_b32_e32 v211, 0xffff0000, v198
	v_and_b32_e32 v245, 0xffff0000, v199
	v_and_b32_e32 v249, 0xffff0000, v200
	v_and_b32_e32 v251, 0xffff0000, v201
	v_pk_mul_f32 v[164:165], v[164:165], s[60:61]
	v_pk_mul_f32 v[170:171], v[170:171], s[60:61]
	v_pk_mul_f32 v[172:173], v[172:173], s[60:61]
	v_pk_mul_f32 v[206:207], v[206:207], s[60:61]
	v_pk_mul_f32 v[210:211], v[210:211], s[60:61]
	v_pk_mul_f32 v[244:245], v[244:245], s[60:61]
	v_pk_mul_f32 v[248:249], v[248:249], s[60:61]
	v_pk_mul_f32 v[250:251], v[250:251], s[60:61]
	v_exp_f32_e32 v164, v164
	v_exp_f32_e32 v170, v170
	v_exp_f32_e32 v172, v172
	v_exp_f32_e32 v206, v206
	v_exp_f32_e32 v165, v165
	v_exp_f32_e32 v171, v171
	v_exp_f32_e32 v173, v173
	v_exp_f32_e32 v207, v207
	v_exp_f32_e32 v210, v210
	v_exp_f32_e32 v244, v244
	v_exp_f32_e32 v248, v248
	v_exp_f32_e32 v250, v250
	v_exp_f32_e32 v211, v211
	v_exp_f32_e32 v245, v245
	v_exp_f32_e32 v249, v249
	v_exp_f32_e32 v251, v251
	v_pk_add_f32 v[164:165], v[164:165], s[78:79]
	v_pk_add_f32 v[170:171], v[170:171], s[78:79]
	v_pk_add_f32 v[172:173], v[172:173], s[78:79]
	v_pk_add_f32 v[206:207], v[206:207], s[78:79]
	v_pk_add_f32 v[210:211], v[210:211], s[78:79]
	v_pk_add_f32 v[244:245], v[244:245], s[78:79]
	v_pk_add_f32 v[248:249], v[248:249], s[78:79]
	v_pk_add_f32 v[250:251], v[250:251], s[78:79]
	v_rcp_f32_e32 v164, v164
	v_rcp_f32_e32 v170, v170
	v_rcp_f32_e32 v172, v172
	v_rcp_f32_e32 v206, v206
	v_rcp_f32_e32 v165, v165
	v_rcp_f32_e32 v171, v171
	v_rcp_f32_e32 v173, v173
	v_rcp_f32_e32 v207, v207
	s_nop 0
	v_pk_mul_f32 v[164:165], v[164:165], v[210:211]
	v_pk_mul_f32 v[170:171], v[170:171], v[244:245]
	v_pk_mul_f32 v[172:173], v[172:173], v[248:249]
	v_pk_mul_f32 v[206:207], v[206:207], v[250:251]
	v_pk_mul_f32 v[20:21], v[20:21], v[164:165]
	v_pk_mul_f32 v[22:23], v[22:23], v[170:171]
	v_pk_mul_f32 v[16:17], v[16:17], v[172:173]
	v_pk_mul_f32 v[18:19], v[18:19], v[206:207]
	s_waitcnt vmcnt(2)
	s_add_u32 s98, s26, 0x58000
	s_addc_u32 s99, s27, 0
	v_lshlrev_b32_e32 v164, 16, v232
	v_lshlrev_b32_e32 v170, 16, v233
	v_lshlrev_b32_e32 v172, 16, v234
	v_lshlrev_b32_e32 v206, 16, v235
	v_and_b32_e32 v165, 0xffff0000, v232
	v_and_b32_e32 v171, 0xffff0000, v233
	v_and_b32_e32 v173, 0xffff0000, v234
	v_and_b32_e32 v207, 0xffff0000, v235
	v_lshlrev_b32_e32 v210, 16, v202
	v_lshlrev_b32_e32 v244, 16, v203
	v_lshlrev_b32_e32 v248, 16, v204
	v_lshlrev_b32_e32 v250, 16, v205
	v_and_b32_e32 v211, 0xffff0000, v202
	v_and_b32_e32 v245, 0xffff0000, v203
	v_and_b32_e32 v249, 0xffff0000, v204
	v_and_b32_e32 v251, 0xffff0000, v205
	v_pk_mul_f32 v[164:165], v[164:165], s[60:61]
	v_pk_mul_f32 v[170:171], v[170:171], s[60:61]
	v_pk_mul_f32 v[172:173], v[172:173], s[60:61]
	v_pk_mul_f32 v[206:207], v[206:207], s[60:61]
	v_pk_mul_f32 v[210:211], v[210:211], s[60:61]
	v_pk_mul_f32 v[244:245], v[244:245], s[60:61]
	v_pk_mul_f32 v[248:249], v[248:249], s[60:61]
	v_pk_mul_f32 v[250:251], v[250:251], s[60:61]
	v_exp_f32_e32 v164, v164
	v_exp_f32_e32 v170, v170
	v_exp_f32_e32 v172, v172
	v_exp_f32_e32 v206, v206
	v_exp_f32_e32 v165, v165
	v_exp_f32_e32 v171, v171
	v_exp_f32_e32 v173, v173
	v_exp_f32_e32 v207, v207
	v_exp_f32_e32 v210, v210
	v_exp_f32_e32 v244, v244
	v_exp_f32_e32 v248, v248
	v_exp_f32_e32 v250, v250
	v_exp_f32_e32 v211, v211
	v_exp_f32_e32 v245, v245
	v_exp_f32_e32 v249, v249
	v_exp_f32_e32 v251, v251
	v_pk_add_f32 v[164:165], v[164:165], s[78:79]
	v_pk_add_f32 v[170:171], v[170:171], s[78:79]
	v_pk_add_f32 v[172:173], v[172:173], s[78:79]
	v_pk_add_f32 v[206:207], v[206:207], s[78:79]
	v_pk_add_f32 v[210:211], v[210:211], s[78:79]
	v_pk_add_f32 v[244:245], v[244:245], s[78:79]
	v_pk_add_f32 v[248:249], v[248:249], s[78:79]
	v_pk_add_f32 v[250:251], v[250:251], s[78:79]
	v_rcp_f32_e32 v164, v164
	v_rcp_f32_e32 v170, v170
	v_rcp_f32_e32 v172, v172
	v_rcp_f32_e32 v206, v206
	v_rcp_f32_e32 v165, v165
	v_rcp_f32_e32 v171, v171
	v_rcp_f32_e32 v173, v173
	v_rcp_f32_e32 v207, v207
	s_nop 0
	v_pk_mul_f32 v[164:165], v[164:165], v[210:211]
	v_pk_mul_f32 v[170:171], v[170:171], v[244:245]
	v_pk_mul_f32 v[172:173], v[172:173], v[248:249]
	v_pk_mul_f32 v[206:207], v[206:207], v[250:251]
	v_pk_mul_f32 v[12:13], v[12:13], v[164:165]
	v_pk_mul_f32 v[14:15], v[14:15], v[170:171]
	v_pk_mul_f32 v[8:9], v[8:9], v[172:173]
	v_pk_mul_f32 v[10:11], v[10:11], v[206:207]
	s_waitcnt vmcnt(0)
	s_add_u32 s98, s26, 0x58000
	s_addc_u32 s99, s27, 0
	v_lshlrev_b32_e32 v164, 16, v236
	v_lshlrev_b32_e32 v170, 16, v237
	v_lshlrev_b32_e32 v172, 16, v238
	v_lshlrev_b32_e32 v206, 16, v239
	v_and_b32_e32 v165, 0xffff0000, v236
	v_and_b32_e32 v171, 0xffff0000, v237
	v_and_b32_e32 v173, 0xffff0000, v238
	v_and_b32_e32 v207, 0xffff0000, v239
	v_lshlrev_b32_e32 v210, 16, v240
	v_lshlrev_b32_e32 v244, 16, v241
	v_lshlrev_b32_e32 v248, 16, v242
	v_lshlrev_b32_e32 v250, 16, v243
	v_and_b32_e32 v211, 0xffff0000, v240
	v_and_b32_e32 v245, 0xffff0000, v241
	v_and_b32_e32 v249, 0xffff0000, v242
	v_and_b32_e32 v251, 0xffff0000, v243
	v_pk_mul_f32 v[164:165], v[164:165], s[60:61]
	v_pk_mul_f32 v[170:171], v[170:171], s[60:61]
	v_pk_mul_f32 v[172:173], v[172:173], s[60:61]
	v_pk_mul_f32 v[206:207], v[206:207], s[60:61]
	v_pk_mul_f32 v[210:211], v[210:211], s[60:61]
	v_pk_mul_f32 v[244:245], v[244:245], s[60:61]
	v_pk_mul_f32 v[248:249], v[248:249], s[60:61]
	v_pk_mul_f32 v[250:251], v[250:251], s[60:61]
	v_exp_f32_e32 v164, v164
	v_exp_f32_e32 v170, v170
	v_exp_f32_e32 v172, v172
	v_exp_f32_e32 v206, v206
	v_exp_f32_e32 v165, v165
	v_exp_f32_e32 v171, v171
	v_exp_f32_e32 v173, v173
	v_exp_f32_e32 v207, v207
	v_exp_f32_e32 v210, v210
	v_exp_f32_e32 v244, v244
	v_exp_f32_e32 v248, v248
	v_exp_f32_e32 v250, v250
	v_exp_f32_e32 v211, v211
	v_exp_f32_e32 v245, v245
	v_exp_f32_e32 v249, v249
	v_exp_f32_e32 v251, v251
	v_pk_add_f32 v[164:165], v[164:165], s[78:79]
	v_pk_add_f32 v[170:171], v[170:171], s[78:79]
	v_pk_add_f32 v[172:173], v[172:173], s[78:79]
	v_pk_add_f32 v[206:207], v[206:207], s[78:79]
	v_pk_add_f32 v[210:211], v[210:211], s[78:79]
	v_pk_add_f32 v[244:245], v[244:245], s[78:79]
	v_pk_add_f32 v[248:249], v[248:249], s[78:79]
	v_pk_add_f32 v[250:251], v[250:251], s[78:79]
	v_rcp_f32_e32 v164, v164
	v_rcp_f32_e32 v170, v170
	v_rcp_f32_e32 v172, v172
	v_rcp_f32_e32 v206, v206
	v_rcp_f32_e32 v165, v165
	v_rcp_f32_e32 v171, v171
	v_rcp_f32_e32 v173, v173
	v_rcp_f32_e32 v207, v207
	s_nop 0
	v_pk_mul_f32 v[164:165], v[164:165], v[210:211]
	v_pk_mul_f32 v[170:171], v[170:171], v[244:245]
	v_pk_mul_f32 v[172:173], v[172:173], v[248:249]
	v_pk_mul_f32 v[206:207], v[206:207], v[250:251]
	v_pk_mul_f32 v[4:5], v[4:5], v[164:165]
	v_pk_mul_f32 v[6:7], v[6:7], v[170:171]
	v_pk_mul_f32 v[0:1], v[0:1], v[172:173]
	v_pk_mul_f32 v[2:3], v[2:3], v[206:207]
	s_branch .Lp6e_done

.LBB0_1873:
	s_load_dwordx2 s[78:79], s[62:63], 0x0
	s_load_dwordx2 s[98:99], s[62:63], 0xb8
	v_lshrrev_b32_e32 v218, 8, v208
	v_and_b32_e32 v219, 15, v208
	v_lshl_add_u32 v218, v218, 6, v219
	v_bfe_u32 v219, v208, 6, 2
	v_bfe_u32 v220, v208, 4, 2
	v_lshlrev_b32_e32 v219, 7, v219
	v_lshl_add_u32 v219, v220, 4, v219
	v_lshl_add_u32 v216, v218, 12, v219
	s_lshl_b32 s0, s43, 20
	s_lshl_b32 s32, s42, 10
	s_add_i32 s0, s0, s32
	s_waitcnt lgkmcnt(0)
	s_cmp_eq_u32 s83, 0
	s_cselect_b32 s18, s78, s98
	s_cselect_b32 s19, s79, s99
	s_add_u32 s18, s18, s0
	s_addc_u32 s19, s19, 0
	s_add_u32 s20, s98, s0
	s_addc_u32 s21, s99, 0
	s_add_u32 s48, s18, 0x0
	s_addc_u32 s49, s19, 0
	global_load_dwordx4 v[140:143], v216, s[48:49]
	s_add_u32 s48, s18, 0x0
	s_addc_u32 s49, s19, 0
	global_load_dwordx4 v[152:155], v216, s[48:49] offset:64
	s_add_u32 s48, s18, 0x0
	s_addc_u32 s49, s19, 0
	global_load_dwordx4 v[156:159], v216, s[48:49] offset:512
	s_add_u32 s48, s18, 0x0
	s_addc_u32 s49, s19, 0
	global_load_dwordx4 v[160:163], v216, s[48:49] offset:576
	s_add_u32 s48, s18, 0x10000
	s_addc_u32 s49, s19, 0
	global_load_dwordx4 v[176:179], v216, s[48:49]
	s_add_u32 s48, s18, 0x10000
	s_addc_u32 s49, s19, 0
	global_load_dwordx4 v[180:183], v216, s[48:49] offset:64
	s_add_u32 s48, s18, 0x10000
	s_addc_u32 s49, s19, 0
	global_load_dwordx4 v[184:187], v216, s[48:49] offset:512
	s_add_u32 s48, s18, 0x10000
	s_addc_u32 s49, s19, 0
	global_load_dwordx4 v[188:191], v216, s[48:49] offset:576
	s_add_u32 s48, s18, 0x20000
	s_addc_u32 s49, s19, 0
	global_load_dwordx4 v[192:195], v216, s[48:49]
	s_add_u32 s48, s18, 0x20000
	s_addc_u32 s49, s19, 0
	global_load_dwordx4 v[196:199], v216, s[48:49] offset:64
	s_add_u32 s48, s18, 0x20000
	s_addc_u32 s49, s19, 0
	global_load_dwordx4 v[200:203], v216, s[48:49] offset:512
	s_add_u32 s48, s18, 0x20000
	s_addc_u32 s49, s19, 0
	global_load_dwordx4 v[204:207], v216, s[48:49] offset:576
	s_add_u32 s48, s18, 0x30000
	s_addc_u32 s49, s19, 0
	global_load_dwordx4 v[224:227], v216, s[48:49]
	s_add_u32 s48, s18, 0x30000
	s_addc_u32 s49, s19, 0
	global_load_dwordx4 v[228:231], v216, s[48:49] offset:64
	s_add_u32 s48, s18, 0x30000
	s_addc_u32 s49, s19, 0
	global_load_dwordx4 v[232:235], v216, s[48:49] offset:512
	s_add_u32 s48, s18, 0x30000
	s_addc_u32 s49, s19, 0
	global_load_dwordx4 v[236:239], v216, s[48:49] offset:576
	s_waitcnt vmcnt(15)
	v_pk_add_f32 v[128:129], v[128:129], v[140:141]
	v_pk_add_f32 v[130:131], v[130:131], v[142:143]
	s_add_u32 s60, s20, 0x0
	s_addc_u32 s61, s21, 0
	global_store_dwordx4 v216, v[128:131], s[60:61]
	s_add_u32 s48, s18, 0x80000
	s_addc_u32 s49, s19, 0
	global_load_dwordx4 v[140:143], v216, s[48:49]
	s_waitcnt vmcnt(16)
	v_pk_add_f32 v[124:125], v[124:125], v[152:153]
	v_pk_add_f32 v[126:127], v[126:127], v[154:155]
	s_add_u32 s60, s20, 0x0
	s_addc_u32 s61, s21, 0
	global_store_dwordx4 v216, v[124:127], s[60:61] offset:64
	s_add_u32 s48, s18, 0x80000
	s_addc_u32 s49, s19, 0
	global_load_dwordx4 v[152:155], v216, s[48:49] offset:64
	s_waitcnt vmcnt(17)
	v_pk_add_f32 v[120:121], v[120:121], v[156:157]
	v_pk_add_f32 v[122:123], v[122:123], v[158:159]
	s_add_u32 s60, s20, 0x0
	s_addc_u32 s61, s21, 0
	global_store_dwordx4 v216, v[120:123], s[60:61] offset:512
	s_add_u32 s48, s18, 0x80000
	s_addc_u32 s49, s19, 0
	global_load_dwordx4 v[156:159], v216, s[48:49] offset:512
	s_waitcnt vmcnt(18)
	v_pk_add_f32 v[116:117], v[116:117], v[160:161]
	v_pk_add_f32 v[118:119], v[118:119], v[162:163]
	s_add_u32 s60, s20, 0x0
	s_addc_u32 s61, s21, 0
	global_store_dwordx4 v216, v[116:119], s[60:61] offset:576
	s_add_u32 s48, s18, 0x80000
	s_addc_u32 s49, s19, 0
	global_load_dwordx4 v[160:163], v216, s[48:49] offset:576
	s_waitcnt vmcnt(19)
	v_pk_add_f32 v[112:113], v[112:113], v[176:177]
	v_pk_add_f32 v[114:115], v[114:115], v[178:179]
	s_add_u32 s60, s20, 0x10000
	s_addc_u32 s61, s21, 0
	global_store_dwordx4 v216, v[112:115], s[60:61]
	s_add_u32 s48, s18, 0x90000
	s_addc_u32 s49, s19, 0
	global_load_dwordx4 v[176:179], v216, s[48:49]
	s_waitcnt vmcnt(20)
	v_pk_add_f32 v[108:109], v[108:109], v[180:181]
	v_pk_add_f32 v[110:111], v[110:111], v[182:183]
	s_add_u32 s60, s20, 0x10000
	s_addc_u32 s61, s21, 0
	global_store_dwordx4 v216, v[108:111], s[60:61] offset:64
	s_add_u32 s48, s18, 0x90000
	s_addc_u32 s49, s19, 0
	global_load_dwordx4 v[180:183], v216, s[48:49] offset:64
	s_waitcnt vmcnt(21)
	v_pk_add_f32 v[104:105], v[104:105], v[184:185]
	v_pk_add_f32 v[106:107], v[106:107], v[186:187]
	s_add_u32 s60, s20, 0x10000
	s_addc_u32 s61, s21, 0
	global_store_dwordx4 v216, v[104:107], s[60:61] offset:512
	s_add_u32 s48, s18, 0x90000
	s_addc_u32 s49, s19, 0
	global_load_dwordx4 v[184:187], v216, s[48:49] offset:512
	s_waitcnt vmcnt(22)
	v_pk_add_f32 v[100:101], v[100:101], v[188:189]
	v_pk_add_f32 v[102:103], v[102:103], v[190:191]
	s_add_u32 s60, s20, 0x10000
	s_addc_u32 s61, s21, 0
	global_store_dwordx4 v216, v[100:103], s[60:61] offset:576
	s_add_u32 s48, s18, 0x90000
	s_addc_u32 s49, s19, 0
	global_load_dwordx4 v[188:191], v216, s[48:49] offset:576
	s_waitcnt vmcnt(23)
	v_pk_add_f32 v[96:97], v[96:97], v[192:193]
	v_pk_add_f32 v[98:99], v[98:99], v[194:195]
	s_add_u32 s60, s20, 0x20000
	s_addc_u32 s61, s21, 0
	global_store_dwordx4 v216, v[96:99], s[60:61]
	s_add_u32 s48, s18, 0xa0000
	s_addc_u32 s49, s19, 0
	global_load_dwordx4 v[192:195], v216, s[48:49]
	s_waitcnt vmcnt(24)
	v_pk_add_f32 v[92:93], v[92:93], v[196:197]
	v_pk_add_f32 v[94:95], v[94:95], v[198:199]
	s_add_u32 s60, s20, 0x20000
	s_addc_u32 s61, s21, 0
	global_store_dwordx4 v216, v[92:95], s[60:61] offset:64
	s_add_u32 s48, s18, 0xa0000
	s_addc_u32 s49, s19, 0
	global_load_dwordx4 v[196:199], v216, s[48:49] offset:64
	s_waitcnt vmcnt(25)
	v_pk_add_f32 v[88:89], v[88:89], v[200:201]
	v_pk_add_f32 v[90:91], v[90:91], v[202:203]
	s_add_u32 s60, s20, 0x20000
	s_addc_u32 s61, s21, 0
	global_store_dwordx4 v216, v[88:91], s[60:61] offset:512
	s_add_u32 s48, s18, 0xa0000
	s_addc_u32 s49, s19, 0
	global_load_dwordx4 v[200:203], v216, s[48:49] offset:512
	s_waitcnt vmcnt(26)
	v_pk_add_f32 v[84:85], v[84:85], v[204:205]
	v_pk_add_f32 v[86:87], v[86:87], v[206:207]
	s_add_u32 s60, s20, 0x20000
	s_addc_u32 s61, s21, 0
	global_store_dwordx4 v216, v[84:87], s[60:61] offset:576
	s_add_u32 s48, s18, 0xa0000
	s_addc_u32 s49, s19, 0
	global_load_dwordx4 v[204:207], v216, s[48:49] offset:576
	s_waitcnt vmcnt(27)
	v_pk_add_f32 v[76:77], v[76:77], v[224:225]
	v_pk_add_f32 v[78:79], v[78:79], v[226:227]
	s_add_u32 s60, s20, 0x30000
	s_addc_u32 s61, s21, 0
	global_store_dwordx4 v216, v[76:79], s[60:61]
	s_add_u32 s48, s18, 0xb0000
	s_addc_u32 s49, s19, 0
	global_load_dwordx4 v[224:227], v216, s[48:49]
	s_waitcnt vmcnt(28)
	v_pk_add_f32 v[72:73], v[72:73], v[228:229]
	v_pk_add_f32 v[74:75], v[74:75], v[230:231]
	s_add_u32 s60, s20, 0x30000
	s_addc_u32 s61, s21, 0
	global_store_dwordx4 v216, v[72:75], s[60:61] offset:64
	s_add_u32 s48, s18, 0xb0000
	s_addc_u32 s49, s19, 0
	global_load_dwordx4 v[228:231], v216, s[48:49] offset:64
	s_waitcnt vmcnt(29)
	v_pk_add_f32 v[68:69], v[68:69], v[232:233]
	v_pk_add_f32 v[70:71], v[70:71], v[234:235]
	s_add_u32 s60, s20, 0x30000
	s_addc_u32 s61, s21, 0
	global_store_dwordx4 v216, v[68:71], s[60:61] offset:512
	s_add_u32 s48, s18, 0xb0000
	s_addc_u32 s49, s19, 0
	global_load_dwordx4 v[232:235], v216, s[48:49] offset:512
	s_waitcnt vmcnt(30)
	v_pk_add_f32 v[64:65], v[64:65], v[236:237]
	v_pk_add_f32 v[66:67], v[66:67], v[238:239]
	s_add_u32 s60, s20, 0x30000
	s_addc_u32 s61, s21, 0
	global_store_dwordx4 v216, v[64:67], s[60:61] offset:576
	s_add_u32 s48, s18, 0xb0000
	s_addc_u32 s49, s19, 0
	global_load_dwordx4 v[236:239], v216, s[48:49] offset:576
	s_waitcnt vmcnt(30)
	v_pk_add_f32 v[60:61], v[60:61], v[140:141]
	v_pk_add_f32 v[62:63], v[62:63], v[142:143]
	s_add_u32 s60, s20, 0x80000
	s_addc_u32 s61, s21, 0
	global_store_dwordx4 v216, v[60:63], s[60:61]
	s_waitcnt vmcnt(29)
	v_pk_add_f32 v[56:57], v[56:57], v[152:153]
	v_pk_add_f32 v[58:59], v[58:59], v[154:155]
	s_add_u32 s60, s20, 0x80000
	s_addc_u32 s61, s21, 0
	global_store_dwordx4 v216, v[56:59], s[60:61] offset:64
	s_waitcnt vmcnt(28)
	v_pk_add_f32 v[52:53], v[52:53], v[156:157]
	v_pk_add_f32 v[54:55], v[54:55], v[158:159]
	s_add_u32 s60, s20, 0x80000
	s_addc_u32 s61, s21, 0
	global_store_dwordx4 v216, v[52:55], s[60:61] offset:512
	s_waitcnt vmcnt(27)
	v_pk_add_f32 v[48:49], v[48:49], v[160:161]
	v_pk_add_f32 v[50:51], v[50:51], v[162:163]
	s_add_u32 s60, s20, 0x80000
	s_addc_u32 s61, s21, 0
	global_store_dwordx4 v216, v[48:51], s[60:61] offset:576
	s_waitcnt vmcnt(26)
	v_pk_add_f32 v[44:45], v[44:45], v[176:177]
	v_pk_add_f32 v[46:47], v[46:47], v[178:179]
	s_add_u32 s60, s20, 0x90000
	s_addc_u32 s61, s21, 0
	global_store_dwordx4 v216, v[44:47], s[60:61]
	s_waitcnt vmcnt(25)
	v_pk_add_f32 v[40:41], v[40:41], v[180:181]
	v_pk_add_f32 v[42:43], v[42:43], v[182:183]
	s_add_u32 s60, s20, 0x90000
	s_addc_u32 s61, s21, 0
	global_store_dwordx4 v216, v[40:43], s[60:61] offset:64
	s_waitcnt vmcnt(24)
	v_pk_add_f32 v[36:37], v[36:37], v[184:185]
	v_pk_add_f32 v[38:39], v[38:39], v[186:187]
	s_add_u32 s60, s20, 0x90000
	s_addc_u32 s61, s21, 0
	global_store_dwordx4 v216, v[36:39], s[60:61] offset:512
	s_waitcnt vmcnt(23)
	v_pk_add_f32 v[32:33], v[32:33], v[188:189]
	v_pk_add_f32 v[34:35], v[34:35], v[190:191]
	s_add_u32 s60, s20, 0x90000
	s_addc_u32 s61, s21, 0
	global_store_dwordx4 v216, v[32:35], s[60:61] offset:576
	s_waitcnt vmcnt(22)
	v_pk_add_f32 v[28:29], v[28:29], v[192:193]
	v_pk_add_f32 v[30:31], v[30:31], v[194:195]
	s_add_u32 s60, s20, 0xa0000
	s_addc_u32 s61, s21, 0
	global_store_dwordx4 v216, v[28:31], s[60:61]
	s_waitcnt vmcnt(21)
	v_pk_add_f32 v[24:25], v[24:25], v[196:197]
	v_pk_add_f32 v[26:27], v[26:27], v[198:199]
	s_add_u32 s60, s20, 0xa0000
	s_addc_u32 s61, s21, 0
	global_store_dwordx4 v216, v[24:27], s[60:61] offset:64
	s_waitcnt vmcnt(20)
	v_pk_add_f32 v[20:21], v[20:21], v[200:201]
	v_pk_add_f32 v[22:23], v[22:23], v[202:203]
	s_add_u32 s60, s20, 0xa0000
	s_addc_u32 s61, s21, 0
	global_store_dwordx4 v216, v[20:23], s[60:61] offset:512
	s_waitcnt vmcnt(19)
	v_pk_add_f32 v[16:17], v[16:17], v[204:205]
	v_pk_add_f32 v[18:19], v[18:19], v[206:207]
	s_add_u32 s60, s20, 0xa0000
	s_addc_u32 s61, s21, 0
	global_store_dwordx4 v216, v[16:19], s[60:61] offset:576
	s_waitcnt vmcnt(18)
	v_pk_add_f32 v[12:13], v[12:13], v[224:225]
	v_pk_add_f32 v[14:15], v[14:15], v[226:227]
	s_add_u32 s60, s20, 0xb0000
	s_addc_u32 s61, s21, 0
	global_store_dwordx4 v216, v[12:15], s[60:61]
	s_waitcnt vmcnt(17)
	v_pk_add_f32 v[8:9], v[8:9], v[228:229]
	v_pk_add_f32 v[10:11], v[10:11], v[230:231]
	s_add_u32 s60, s20, 0xb0000
	s_addc_u32 s61, s21, 0
	global_store_dwordx4 v216, v[8:11], s[60:61] offset:64
	s_waitcnt vmcnt(16)
	v_pk_add_f32 v[4:5], v[4:5], v[232:233]
	v_pk_add_f32 v[6:7], v[6:7], v[234:235]
	s_add_u32 s60, s20, 0xb0000
	s_addc_u32 s61, s21, 0
	global_store_dwordx4 v216, v[4:7], s[60:61] offset:512
	s_waitcnt vmcnt(15)
	v_pk_add_f32 v[0:1], v[0:1], v[236:237]
	v_pk_add_f32 v[2:3], v[2:3], v[238:239]
	s_add_u32 s60, s20, 0xb0000
	s_addc_u32 s61, s21, 0
	global_store_dwordx4 v216, v[0:3], s[60:61] offset:576
	s_branch .Lp7e_done
	v_lshl_add_u32 v170, s43, 8, v146
	v_lshl_or_b32 v140, s42, 8, v148
	v_ashrrev_i32_e32 v141, 31, v140
	v_or_b32_e32 v172, 16, v170
	v_lshlrev_b64 v[140:141], 2, v[140:141]
	v_ashrrev_i32_e32 v171, 31, v170
	v_ashrrev_i32_e32 v173, 31, v172
	v_lshl_add_u64 v[142:143], v[212:213], 0, v[140:141]
	v_lshlrev_b64 v[144:145], 12, v[170:171]
	v_lshlrev_b64 v[172:173], 12, v[172:173]
	v_lshl_add_u64 v[162:163], v[142:143], 0, v[144:145]
	v_lshl_add_u64 v[188:189], v[142:143], 0, v[172:173]
	global_load_dwordx4 v[150:153], v[162:163], off
	global_load_dwordx4 v[154:157], v[162:163], off offset:64
	global_load_dwordx4 v[158:161], v[162:163], off offset:512
	s_nop 0
	global_load_dwordx4 v[162:165], v[162:163], off offset:576
	s_nop 0
	global_load_dwordx4 v[176:179], v[188:189], off
	global_load_dwordx4 v[180:183], v[188:189], off offset:64
	global_load_dwordx4 v[184:187], v[188:189], off offset:512
	s_nop 0
	global_load_dwordx4 v[188:191], v[188:189], off offset:576
	s_waitcnt vmcnt(0)
	v_pk_add_f32 v[128:129], v[128:129], v[150:151]
	v_lshl_add_u64 v[150:151], v[132:133], 0, v[144:145]
	v_lshl_add_u64 v[150:151], v[150:151], 0, v[140:141]
	v_pk_add_f32 v[118:119], v[118:119], v[164:165]
	v_pk_add_f32 v[116:117], v[116:117], v[162:163]
	global_store_dwordx4 v[150:151], v[116:119], off offset:576
	v_pk_add_f32 v[130:131], v[130:131], v[152:153]
	v_pk_add_f32 v[126:127], v[126:127], v[156:157]
	v_lshl_add_u64 v[116:117], v[132:133], 0, v[172:173]
	v_pk_add_f32 v[124:125], v[124:125], v[154:155]
	v_pk_add_f32 v[122:123], v[122:123], v[160:161]
	v_pk_add_f32 v[120:121], v[120:121], v[158:159]
	v_pk_add_f32 v[114:115], v[114:115], v[178:179]
	v_pk_add_f32 v[112:113], v[112:113], v[176:177]
	v_lshl_add_u64 v[116:117], v[116:117], 0, v[140:141]
	v_pk_add_f32 v[110:111], v[110:111], v[182:183]
	v_pk_add_f32 v[108:109], v[108:109], v[180:181]
	v_pk_add_f32 v[106:107], v[106:107], v[186:187]
	v_pk_add_f32 v[104:105], v[104:105], v[184:185]
	v_pk_add_f32 v[102:103], v[102:103], v[190:191]
	v_pk_add_f32 v[100:101], v[100:101], v[188:189]
	global_store_dwordx4 v[150:151], v[128:131], off
	global_store_dwordx4 v[150:151], v[124:127], off offset:64
	global_store_dwordx4 v[150:151], v[120:123], off offset:512
	global_store_dwordx4 v[116:117], v[112:115], off
	global_store_dwordx4 v[116:117], v[108:111], off offset:64
	global_store_dwordx4 v[116:117], v[104:107], off offset:512
	global_store_dwordx4 v[116:117], v[100:103], off offset:576
	s_nop 1
	v_or_b32_e32 v100, 32, v170
	v_or_b32_e32 v116, 48, v170
	v_ashrrev_i32_e32 v101, 31, v100
	v_ashrrev_i32_e32 v117, 31, v116
	v_lshlrev_b64 v[150:151], 12, v[100:101]
	v_lshlrev_b64 v[152:153], 12, v[116:117]
	v_lshl_add_u64 v[112:113], v[142:143], 0, v[150:151]
	v_lshl_add_u64 v[128:129], v[142:143], 0, v[152:153]
	global_load_dwordx4 v[100:103], v[112:113], off
	global_load_dwordx4 v[104:107], v[112:113], off offset:64
	global_load_dwordx4 v[108:111], v[112:113], off offset:512
	s_nop 0
	global_load_dwordx4 v[112:115], v[112:113], off offset:576
	s_nop 0
	global_load_dwordx4 v[116:119], v[128:129], off
	global_load_dwordx4 v[120:123], v[128:129], off offset:64
	global_load_dwordx4 v[124:127], v[128:129], off offset:512
	s_nop 0
	global_load_dwordx4 v[128:131], v[128:129], off offset:576
	s_waitcnt vmcnt(0)
	v_pk_add_f32 v[96:97], v[96:97], v[100:101]
	v_lshl_add_u64 v[100:101], v[132:133], 0, v[150:151]
	v_lshl_add_u64 v[100:101], v[100:101], 0, v[140:141]
	v_pk_add_f32 v[86:87], v[86:87], v[114:115]
	v_pk_add_f32 v[84:85], v[84:85], v[112:113]
	global_store_dwordx4 v[100:101], v[84:87], off offset:576
	v_pk_add_f32 v[98:99], v[98:99], v[102:103]
	v_pk_add_f32 v[94:95], v[94:95], v[106:107]
	v_lshl_add_u64 v[84:85], v[132:133], 0, v[152:153]
	v_pk_add_f32 v[92:93], v[92:93], v[104:105]
	v_pk_add_f32 v[90:91], v[90:91], v[110:111]
	v_pk_add_f32 v[88:89], v[88:89], v[108:109]
	v_pk_add_f32 v[78:79], v[78:79], v[118:119]
	v_pk_add_f32 v[76:77], v[76:77], v[116:117]
	v_lshl_add_u64 v[84:85], v[84:85], 0, v[140:141]
	v_pk_add_f32 v[74:75], v[74:75], v[122:123]
	v_pk_add_f32 v[72:73], v[72:73], v[120:121]
	v_pk_add_f32 v[70:71], v[70:71], v[126:127]
	v_pk_add_f32 v[68:69], v[68:69], v[124:125]
	v_pk_add_f32 v[66:67], v[66:67], v[130:131]
	v_pk_add_f32 v[64:65], v[64:65], v[128:129]
	global_store_dwordx4 v[100:101], v[96:99], off
	global_store_dwordx4 v[100:101], v[92:95], off offset:64
	global_store_dwordx4 v[100:101], v[88:91], off offset:512
	global_store_dwordx4 v[84:85], v[76:79], off
	global_store_dwordx4 v[84:85], v[72:75], off offset:64
	global_store_dwordx4 v[84:85], v[68:71], off offset:512
	global_store_dwordx4 v[84:85], v[64:67], off offset:576
	s_mov_b64 s[18:19], 0x80000
	v_lshl_add_u64 v[100:101], v[144:145], 0, s[18:19]
	s_mov_b64 s[18:19], 0x90000
	v_lshl_add_u64 v[102:103], v[144:145], 0, s[18:19]
	v_lshl_add_u64 v[76:77], v[142:143], 0, v[100:101]
	v_lshl_add_u64 v[96:97], v[142:143], 0, v[102:103]
	global_load_dwordx4 v[64:67], v[76:77], off
	global_load_dwordx4 v[68:71], v[76:77], off offset:64
	global_load_dwordx4 v[72:75], v[76:77], off offset:512
	s_nop 0
	global_load_dwordx4 v[76:79], v[76:77], off offset:576
	s_nop 0
	global_load_dwordx4 v[84:87], v[96:97], off
	global_load_dwordx4 v[88:91], v[96:97], off offset:64
	global_load_dwordx4 v[92:95], v[96:97], off offset:512
	s_nop 0
	global_load_dwordx4 v[96:99], v[96:97], off offset:576
	s_waitcnt vmcnt(0)
	v_pk_add_f32 v[60:61], v[60:61], v[64:65]
	v_lshl_add_u64 v[64:65], v[132:133], 0, v[100:101]
	v_lshl_add_u64 v[64:65], v[64:65], 0, v[140:141]
	v_pk_add_f32 v[50:51], v[50:51], v[78:79]
	v_pk_add_f32 v[48:49], v[48:49], v[76:77]
	global_store_dwordx4 v[64:65], v[48:51], off offset:576
	v_pk_add_f32 v[62:63], v[62:63], v[66:67]
	v_pk_add_f32 v[58:59], v[58:59], v[70:71]
	v_lshl_add_u64 v[48:49], v[132:133], 0, v[102:103]
	v_pk_add_f32 v[56:57], v[56:57], v[68:69]
	v_pk_add_f32 v[54:55], v[54:55], v[74:75]
	v_pk_add_f32 v[52:53], v[52:53], v[72:73]
	v_pk_add_f32 v[46:47], v[46:47], v[86:87]
	v_pk_add_f32 v[44:45], v[44:45], v[84:85]
	v_lshl_add_u64 v[48:49], v[48:49], 0, v[140:141]
	v_pk_add_f32 v[42:43], v[42:43], v[90:91]
	v_pk_add_f32 v[40:41], v[40:41], v[88:89]
	v_pk_add_f32 v[38:39], v[38:39], v[94:95]
	v_pk_add_f32 v[36:37], v[36:37], v[92:93]
	v_pk_add_f32 v[34:35], v[34:35], v[98:99]
	v_pk_add_f32 v[32:33], v[32:33], v[96:97]
	global_store_dwordx4 v[64:65], v[60:63], off
	global_store_dwordx4 v[64:65], v[56:59], off offset:64
	global_store_dwordx4 v[64:65], v[52:55], off offset:512
	global_store_dwordx4 v[48:49], v[44:47], off
	global_store_dwordx4 v[48:49], v[40:43], off offset:64
	global_store_dwordx4 v[48:49], v[36:39], off offset:512
	global_store_dwordx4 v[48:49], v[32:35], off offset:576
	s_mov_b64 s[18:19], 0xa0000
	v_lshl_add_u64 v[64:65], v[144:145], 0, s[18:19]
	s_mov_b64 s[18:19], 0xb0000
	v_lshl_add_u64 v[66:67], v[144:145], 0, s[18:19]
	v_lshl_add_u64 v[44:45], v[142:143], 0, v[64:65]
	v_lshl_add_u64 v[60:61], v[142:143], 0, v[66:67]
	global_load_dwordx4 v[32:35], v[44:45], off
	global_load_dwordx4 v[36:39], v[44:45], off offset:64
	global_load_dwordx4 v[40:43], v[44:45], off offset:512
	s_nop 0
	global_load_dwordx4 v[44:47], v[44:45], off offset:576
	s_nop 0
	global_load_dwordx4 v[48:51], v[60:61], off
	global_load_dwordx4 v[52:55], v[60:61], off offset:64
	global_load_dwordx4 v[56:59], v[60:61], off offset:512
	s_nop 0
	global_load_dwordx4 v[60:63], v[60:61], off offset:576
	s_waitcnt vmcnt(0)
	v_pk_add_f32 v[28:29], v[28:29], v[32:33]
	v_lshl_add_u64 v[32:33], v[132:133], 0, v[64:65]
	v_lshl_add_u64 v[32:33], v[32:33], 0, v[140:141]
	v_pk_add_f32 v[18:19], v[18:19], v[46:47]
	v_pk_add_f32 v[16:17], v[16:17], v[44:45]
	global_store_dwordx4 v[32:33], v[16:19], off offset:576
	v_pk_add_f32 v[30:31], v[30:31], v[34:35]
	v_pk_add_f32 v[26:27], v[26:27], v[38:39]
	v_lshl_add_u64 v[16:17], v[132:133], 0, v[66:67]
	v_pk_add_f32 v[24:25], v[24:25], v[36:37]
	v_pk_add_f32 v[22:23], v[22:23], v[42:43]
	v_pk_add_f32 v[20:21], v[20:21], v[40:41]
	v_pk_add_f32 v[14:15], v[14:15], v[50:51]
	v_pk_add_f32 v[12:13], v[12:13], v[48:49]
	v_lshl_add_u64 v[16:17], v[16:17], 0, v[140:141]
	v_pk_add_f32 v[10:11], v[10:11], v[54:55]
	v_pk_add_f32 v[8:9], v[8:9], v[52:53]
	v_pk_add_f32 v[6:7], v[6:7], v[58:59]
	v_pk_add_f32 v[4:5], v[4:5], v[56:57]
	v_pk_add_f32 v[2:3], v[2:3], v[62:63]
	v_pk_add_f32 v[0:1], v[0:1], v[60:61]
	global_store_dwordx4 v[32:33], v[28:31], off
	global_store_dwordx4 v[32:33], v[24:27], off offset:64
	global_store_dwordx4 v[32:33], v[20:23], off offset:512
	global_store_dwordx4 v[16:17], v[12:15], off
	global_store_dwordx4 v[16:17], v[8:11], off offset:64
	global_store_dwordx4 v[16:17], v[4:7], off offset:512
	global_store_dwordx4 v[16:17], v[0:3], off offset:576
.Lp7e_done:
	s_and_b64 vcc, exec, s[6:7]
	s_mov_b32 s42, s40
	s_mov_b32 s43, s41
	s_mov_b64 s[20:21], s[8:9]
	s_mov_b64 s[18:19], s[10:11]
	s_cbranch_vccnz .LBB0_1888
